# speedup vs baseline: 1.1386x; 1.0075x over previous
.LBB0_1081:
	s_andn2_b64 vcc, exec, s[4:5]
	s_cbranch_vccnz .LBB0_1090
	v_mov_b32_e32 v0, v135
	s_mov_b32 s4, s2
	v_ashrrev_i32_e32 v1, 2, v0
	v_and_b32_e32 v1, -16, v1
	s_nop 0
	v_lshl_add_u32 v64, s4, 7, v1
	v_cmp_gt_i32_e32 vcc, s60, v64
	s_and_saveexec_b64 s[4:5], vcc
	s_cbranch_execz .LBB0_1089
	v_readfirstlane_b32 s24, v64
	s_load_dwordx2 s[8:9], s[0:1], 0x68
	s_load_dwordx2 s[22:23], s[0:1], 0x8
	s_load_dword s25, s[72:73], 0x0
	v_readlane_b32 s6, v247, 19
	v_readlane_b32 s7, v247, 20
	v_readlane_b32 s12, v246, 26
	v_readlane_b32 s13, v246, 27
	s_mul_i32 s26, s70, 0x6000
	s_lshl_b32 s27, s58, 12
	v_and_b32_e32 v196, 63, v135
	v_lshlrev_b32_e32 v197, 4, v196
	v_lshlrev_b32_e32 v198, 3, v196
	v_mov_b32_e32 v194, 0x3a800000
	v_mov_b32_e32 v195, 0x358637bd
	s_waitcnt lgkmcnt(0)
	s_add_u32 s20, s8, s26
	s_addc_u32 s21, s9, 0
	s_add_u32 s22, s22, s27
	s_addc_u32 s23, s23, 0
	s_lshl_b32 s25, s25, 7
	global_load_dwordx4 v[0:3], v197, s[22:23]
	global_load_dwordx4 v[4:7], v197, s[22:23] offset:1024
	global_load_dwordx4 v[8:11], v197, s[22:23] offset:2048
	global_load_dwordx4 v[12:15], v197, s[22:23] offset:3072
	global_load_dwordx4 v[16:19], v197, s[20:21]
	global_load_dwordx4 v[20:23], v197, s[20:21] offset:1024
	global_load_dwordx4 v[24:27], v197, s[20:21] offset:2048
	global_load_dwordx4 v[28:31], v197, s[20:21] offset:3072
	s_add_u32 s20, s20, 0x1000
	s_addc_u32 s21, s21, 0
	global_load_dwordx4 v[32:35], v197, s[20:21]
	global_load_dwordx4 v[36:39], v197, s[20:21] offset:1024
	global_load_dwordx4 v[40:43], v197, s[20:21] offset:2048
	global_load_dwordx4 v[44:47], v197, s[20:21] offset:3072
	s_add_u32 s8, s6, 0x4000000
	s_addc_u32 s9, s7, 0
	s_add_u32 s10, s6, 0x8000000
	s_addc_u32 s11, s7, 0
.Lnm_outer:
	s_and_b32 s26, s24, 0x3fff
	s_cmp_lg_u32 s26, 0
	s_cselect_b32 s26, 1, 0
	s_sub_i32 s27, s24, s26
	s_lshl_b32 s27, s27, 12
	v_add_u32_e32 v199, s27, v197
	s_lshl_b32 s27, s24, 11
	v_add_u32_e32 v200, s27, v198
	global_load_dwordx4 v[48:51], v199, s[12:13]
	global_load_dwordx4 v[52:55], v199, s[12:13] offset:1024
	global_load_dwordx4 v[56:59], v199, s[12:13] offset:2048
	global_load_dwordx4 v[60:63], v199, s[12:13] offset:3072
	v_add_u32_e32 v199, 0x1000, v199
	s_cmp_eq_u32 s26, 0
	s_cbranch_scc1 .Lnm_nolook
	s_waitcnt vmcnt(0)
	global_load_dwordx4 v[64:67], v199, s[12:13]
	global_load_dwordx4 v[68:71], v199, s[12:13] offset:1024
	global_load_dwordx4 v[72:75], v199, s[12:13] offset:2048
	global_load_dwordx4 v[76:79], v199, s[12:13] offset:3072
	v_add_u32_e32 v199, 0x1000, v199
	v_pk_mul_f32 v[128:129], v[48:49], v[48:49]
	v_pk_fma_f32 v[128:129], v[50:51], v[50:51], v[128:129]
	v_pk_fma_f32 v[128:129], v[52:53], v[52:53], v[128:129]
	v_pk_fma_f32 v[128:129], v[54:55], v[54:55], v[128:129]
	v_pk_fma_f32 v[128:129], v[56:57], v[56:57], v[128:129]
	v_pk_fma_f32 v[128:129], v[58:59], v[58:59], v[128:129]
	v_pk_fma_f32 v[128:129], v[60:61], v[60:61], v[128:129]
	v_pk_fma_f32 v[128:129], v[62:63], v[62:63], v[128:129]
	s_nop 0
	v_add_f32_e32 v128, v128, v129
	s_nop 1
	v_add_f32_dpp v128, v128, v128 quad_perm:[1,0,3,2] row_mask:0xf bank_mask:0xf bound_ctrl:1
	s_nop 1
	v_add_f32_dpp v128, v128, v128 quad_perm:[2,3,0,1] row_mask:0xf bank_mask:0xf bound_ctrl:1
	s_nop 1
	v_add_f32_dpp v128, v128, v128 row_half_mirror row_mask:0xf bank_mask:0xf bound_ctrl:1
	s_nop 1
	v_add_f32_dpp v128, v128, v128 row_mirror row_mask:0xf bank_mask:0xf bound_ctrl:1
	s_nop 1
	v_readlane_b32 s20, v128, 0
	v_readlane_b32 s21, v128, 32
	v_readlane_b32 s22, v128, 16
	v_readlane_b32 s23, v128, 48
	s_nop 1
	v_mov_b32_e32 v130, s22
	v_mov_b32_e32 v131, s23
	v_pk_add_f32 v[130:131], s[20:21], v[130:131]
	s_nop 0
	v_add_f32_e32 v130, v130, v131
	v_fma_f32 v130, v130, v194, v195
	v_rsq_f32_e32 v130, v130
	s_nop 0
	v_pk_mul_f32 v[96:97], v[48:49], v[130:131] op_sel_hi:[1,0]
	v_pk_mul_f32 v[98:99], v[50:51], v[130:131] op_sel_hi:[1,0]
	v_pk_mul_f32 v[100:101], v[52:53], v[130:131] op_sel_hi:[1,0]
	v_pk_mul_f32 v[102:103], v[54:55], v[130:131] op_sel_hi:[1,0]
	v_pk_mul_f32 v[104:105], v[56:57], v[130:131] op_sel_hi:[1,0]
	v_pk_mul_f32 v[106:107], v[58:59], v[130:131] op_sel_hi:[1,0]
	v_pk_mul_f32 v[108:109], v[60:61], v[130:131] op_sel_hi:[1,0]
	v_pk_mul_f32 v[110:111], v[62:63], v[130:131] op_sel_hi:[1,0]
	v_pk_mul_f32 v[96:97], v[0:1], v[96:97]
	v_pk_mul_f32 v[98:99], v[2:3], v[98:99]
	v_pk_mul_f32 v[100:101], v[4:5], v[100:101]
	v_pk_mul_f32 v[102:103], v[6:7], v[102:103]
	v_pk_mul_f32 v[104:105], v[8:9], v[104:105]
	v_pk_mul_f32 v[106:107], v[10:11], v[106:107]
	v_pk_mul_f32 v[108:109], v[12:13], v[108:109]
	v_pk_mul_f32 v[110:111], v[14:15], v[110:111]
	v_cvt_pk_bf16_f32 v170, v96, v97
	v_cvt_pk_bf16_f32 v171, v98, v99
	v_cvt_pk_bf16_f32 v172, v100, v101
	v_cvt_pk_bf16_f32 v173, v102, v103
	v_cvt_pk_bf16_f32 v174, v104, v105
	v_cvt_pk_bf16_f32 v175, v106, v107
	v_cvt_pk_bf16_f32 v176, v108, v109
	v_cvt_pk_bf16_f32 v177, v110, v111
	v_lshlrev_b32_e32 v136, 16, v170
	v_and_b32_e32 v137, 0xffff0000, v170
	v_lshlrev_b32_e32 v138, 16, v171
	v_and_b32_e32 v139, 0xffff0000, v171
	v_lshlrev_b32_e32 v140, 16, v172
	v_and_b32_e32 v141, 0xffff0000, v172
	v_lshlrev_b32_e32 v142, 16, v173
	v_and_b32_e32 v143, 0xffff0000, v173
	v_lshlrev_b32_e32 v144, 16, v174
	v_and_b32_e32 v145, 0xffff0000, v174
	v_lshlrev_b32_e32 v146, 16, v175
	v_and_b32_e32 v147, 0xffff0000, v175
	v_lshlrev_b32_e32 v148, 16, v176
	v_and_b32_e32 v149, 0xffff0000, v176
	v_lshlrev_b32_e32 v150, 16, v177
	v_and_b32_e32 v151, 0xffff0000, v177
	s_branch .Lnm_rows
.Lnm_nolook:
	v_mov_b32_e32 v136, 0
	v_mov_b32_e32 v137, 0
	v_mov_b32_e32 v138, 0
	v_mov_b32_e32 v139, 0
	v_mov_b32_e32 v140, 0
	v_mov_b32_e32 v141, 0
	v_mov_b32_e32 v142, 0
	v_mov_b32_e32 v143, 0
	v_mov_b32_e32 v144, 0
	v_mov_b32_e32 v145, 0
	v_mov_b32_e32 v146, 0
	v_mov_b32_e32 v147, 0
	v_mov_b32_e32 v148, 0
	v_mov_b32_e32 v149, 0
	v_mov_b32_e32 v150, 0
	v_mov_b32_e32 v151, 0
	s_waitcnt vmcnt(0)
	v_mov_b64_e32 v[64:65], v[48:49]
	v_mov_b64_e32 v[66:67], v[50:51]
	v_mov_b64_e32 v[68:69], v[52:53]
	v_mov_b64_e32 v[70:71], v[54:55]
	v_mov_b64_e32 v[72:73], v[56:57]
	v_mov_b64_e32 v[74:75], v[58:59]
	v_mov_b64_e32 v[76:77], v[60:61]
	v_mov_b64_e32 v[78:79], v[62:63]
.Lnm_rows:
	s_waitcnt vmcnt(0)
	global_load_dwordx4 v[48:51], v199, s[12:13]
	global_load_dwordx4 v[52:55], v199, s[12:13] offset:1024
	global_load_dwordx4 v[56:59], v199, s[12:13] offset:2048
	global_load_dwordx4 v[60:63], v199, s[12:13] offset:3072
	v_add_u32_e32 v199, 0x1000, v199
	v_pk_mul_f32 v[128:129], v[64:65], v[64:65]
	v_pk_fma_f32 v[128:129], v[66:67], v[66:67], v[128:129]
	v_pk_fma_f32 v[128:129], v[68:69], v[68:69], v[128:129]
	v_pk_fma_f32 v[128:129], v[70:71], v[70:71], v[128:129]
	v_pk_fma_f32 v[128:129], v[72:73], v[72:73], v[128:129]
	v_pk_fma_f32 v[128:129], v[74:75], v[74:75], v[128:129]
	v_pk_fma_f32 v[128:129], v[76:77], v[76:77], v[128:129]
	v_pk_fma_f32 v[128:129], v[78:79], v[78:79], v[128:129]
	s_nop 0
	v_add_f32_e32 v128, v128, v129
	s_nop 1
	v_add_f32_dpp v128, v128, v128 quad_perm:[1,0,3,2] row_mask:0xf bank_mask:0xf bound_ctrl:1
	s_nop 1
	v_add_f32_dpp v128, v128, v128 quad_perm:[2,3,0,1] row_mask:0xf bank_mask:0xf bound_ctrl:1
	s_nop 1
	v_add_f32_dpp v128, v128, v128 row_half_mirror row_mask:0xf bank_mask:0xf bound_ctrl:1
	s_nop 1
	v_add_f32_dpp v128, v128, v128 row_mirror row_mask:0xf bank_mask:0xf bound_ctrl:1
	s_nop 1
	v_readlane_b32 s20, v128, 0
	v_readlane_b32 s21, v128, 32
	v_readlane_b32 s22, v128, 16
	v_readlane_b32 s23, v128, 48
	s_nop 1
	v_mov_b32_e32 v130, s22
	v_mov_b32_e32 v131, s23
	v_pk_add_f32 v[130:131], s[20:21], v[130:131]
	s_nop 0
	v_add_f32_e32 v130, v130, v131
	v_fma_f32 v130, v130, v194, v195
	v_rsq_f32_e32 v130, v130
	s_nop 0
	v_pk_mul_f32 v[96:97], v[64:65], v[130:131] op_sel_hi:[1,0]
	v_pk_mul_f32 v[98:99], v[66:67], v[130:131] op_sel_hi:[1,0]
	v_pk_mul_f32 v[100:101], v[68:69], v[130:131] op_sel_hi:[1,0]
	v_pk_mul_f32 v[102:103], v[70:71], v[130:131] op_sel_hi:[1,0]
	v_pk_mul_f32 v[104:105], v[72:73], v[130:131] op_sel_hi:[1,0]
	v_pk_mul_f32 v[106:107], v[74:75], v[130:131] op_sel_hi:[1,0]
	v_pk_mul_f32 v[108:109], v[76:77], v[130:131] op_sel_hi:[1,0]
	v_pk_mul_f32 v[110:111], v[78:79], v[130:131] op_sel_hi:[1,0]
	v_pk_mul_f32 v[96:97], v[0:1], v[96:97]
	v_pk_mul_f32 v[98:99], v[2:3], v[98:99]
	v_pk_mul_f32 v[100:101], v[4:5], v[100:101]
	v_pk_mul_f32 v[102:103], v[6:7], v[102:103]
	v_pk_mul_f32 v[104:105], v[8:9], v[104:105]
	v_pk_mul_f32 v[106:107], v[10:11], v[106:107]
	v_pk_mul_f32 v[108:109], v[12:13], v[108:109]
	v_pk_mul_f32 v[110:111], v[14:15], v[110:111]
	v_cvt_pk_bf16_f32 v170, v96, v97
	v_cvt_pk_bf16_f32 v171, v98, v99
	v_cvt_pk_bf16_f32 v172, v100, v101
	v_cvt_pk_bf16_f32 v173, v102, v103
	v_cvt_pk_bf16_f32 v174, v104, v105
	v_cvt_pk_bf16_f32 v175, v106, v107
	v_cvt_pk_bf16_f32 v176, v108, v109
	v_cvt_pk_bf16_f32 v177, v110, v111
	v_lshlrev_b32_e32 v80, 16, v170
	v_and_b32_e32 v81, 0xffff0000, v170
	v_lshlrev_b32_e32 v82, 16, v171
	v_and_b32_e32 v83, 0xffff0000, v171
	v_lshlrev_b32_e32 v84, 16, v172
	v_and_b32_e32 v85, 0xffff0000, v172
	v_lshlrev_b32_e32 v86, 16, v173
	v_and_b32_e32 v87, 0xffff0000, v173
	v_lshlrev_b32_e32 v88, 16, v174
	v_and_b32_e32 v89, 0xffff0000, v174
	v_lshlrev_b32_e32 v90, 16, v175
	v_and_b32_e32 v91, 0xffff0000, v175
	v_lshlrev_b32_e32 v92, 16, v176
	v_and_b32_e32 v93, 0xffff0000, v176
	v_lshlrev_b32_e32 v94, 16, v177
	v_and_b32_e32 v95, 0xffff0000, v177
	v_pk_add_f32 v[112:113], v[136:137], v[80:81] neg_lo:[0,1] neg_hi:[0,1]
	v_pk_add_f32 v[114:115], v[138:139], v[82:83] neg_lo:[0,1] neg_hi:[0,1]
	v_pk_add_f32 v[116:117], v[140:141], v[84:85] neg_lo:[0,1] neg_hi:[0,1]
	v_pk_add_f32 v[118:119], v[142:143], v[86:87] neg_lo:[0,1] neg_hi:[0,1]
	v_pk_add_f32 v[120:121], v[144:145], v[88:89] neg_lo:[0,1] neg_hi:[0,1]
	v_pk_add_f32 v[122:123], v[146:147], v[90:91] neg_lo:[0,1] neg_hi:[0,1]
	v_pk_add_f32 v[124:125], v[148:149], v[92:93] neg_lo:[0,1] neg_hi:[0,1]
	v_pk_add_f32 v[126:127], v[150:151], v[94:95] neg_lo:[0,1] neg_hi:[0,1]
	global_store_dwordx2 v200, v[170:171], s[10:11]
	global_store_dwordx2 v200, v[172:173], s[10:11] offset:512
	global_store_dwordx2 v200, v[174:175], s[10:11] offset:1024
	global_store_dwordx2 v200, v[176:177], s[10:11] offset:1536
	v_pk_fma_f32 v[96:97], v[112:113], v[16:17], v[80:81]
	v_pk_fma_f32 v[98:99], v[114:115], v[18:19], v[82:83]
	v_pk_fma_f32 v[100:101], v[116:117], v[20:21], v[84:85]
	v_pk_fma_f32 v[102:103], v[118:119], v[22:23], v[86:87]
	v_pk_fma_f32 v[104:105], v[120:121], v[24:25], v[88:89]
	v_pk_fma_f32 v[106:107], v[122:123], v[26:27], v[90:91]
	v_pk_fma_f32 v[108:109], v[124:125], v[28:29], v[92:93]
	v_pk_fma_f32 v[110:111], v[126:127], v[30:31], v[94:95]
	v_cvt_pk_bf16_f32 v178, v96, v97
	v_cvt_pk_bf16_f32 v179, v98, v99
	v_cvt_pk_bf16_f32 v180, v100, v101
	v_cvt_pk_bf16_f32 v181, v102, v103
	v_cvt_pk_bf16_f32 v182, v104, v105
	v_cvt_pk_bf16_f32 v183, v106, v107
	v_cvt_pk_bf16_f32 v184, v108, v109
	v_cvt_pk_bf16_f32 v185, v110, v111
	global_store_dwordx2 v200, v[178:179], s[6:7]
	global_store_dwordx2 v200, v[180:181], s[6:7] offset:512
	global_store_dwordx2 v200, v[182:183], s[6:7] offset:1024
	global_store_dwordx2 v200, v[184:185], s[6:7] offset:1536
	v_pk_fma_f32 v[96:97], v[112:113], v[32:33], v[80:81]
	v_pk_fma_f32 v[98:99], v[114:115], v[34:35], v[82:83]
	v_pk_fma_f32 v[100:101], v[116:117], v[36:37], v[84:85]
	v_pk_fma_f32 v[102:103], v[118:119], v[38:39], v[86:87]
	v_pk_fma_f32 v[104:105], v[120:121], v[40:41], v[88:89]
	v_pk_fma_f32 v[106:107], v[122:123], v[42:43], v[90:91]
	v_pk_fma_f32 v[108:109], v[124:125], v[44:45], v[92:93]
	v_pk_fma_f32 v[110:111], v[126:127], v[46:47], v[94:95]
	v_cvt_pk_bf16_f32 v186, v96, v97
	v_cvt_pk_bf16_f32 v187, v98, v99
	v_cvt_pk_bf16_f32 v188, v100, v101
	v_cvt_pk_bf16_f32 v189, v102, v103
	v_cvt_pk_bf16_f32 v190, v104, v105
	v_cvt_pk_bf16_f32 v191, v106, v107
	v_cvt_pk_bf16_f32 v192, v108, v109
	v_cvt_pk_bf16_f32 v193, v110, v111
	global_store_dwordx2 v200, v[186:187], s[8:9]
	global_store_dwordx2 v200, v[188:189], s[8:9] offset:512
	global_store_dwordx2 v200, v[190:191], s[8:9] offset:1024
	global_store_dwordx2 v200, v[192:193], s[8:9] offset:1536
	v_add_u32_e32 v200, 0x800, v200
	s_waitcnt vmcnt(12)
	global_load_dwordx4 v[64:67], v199, s[12:13]
	global_load_dwordx4 v[68:71], v199, s[12:13] offset:1024
	global_load_dwordx4 v[72:75], v199, s[12:13] offset:2048
	global_load_dwordx4 v[76:79], v199, s[12:13] offset:3072
	v_add_u32_e32 v199, 0x1000, v199
	v_pk_mul_f32 v[128:129], v[48:49], v[48:49]
	v_pk_fma_f32 v[128:129], v[50:51], v[50:51], v[128:129]
	v_pk_fma_f32 v[128:129], v[52:53], v[52:53], v[128:129]
	v_pk_fma_f32 v[128:129], v[54:55], v[54:55], v[128:129]
	v_pk_fma_f32 v[128:129], v[56:57], v[56:57], v[128:129]
	v_pk_fma_f32 v[128:129], v[58:59], v[58:59], v[128:129]
	v_pk_fma_f32 v[128:129], v[60:61], v[60:61], v[128:129]
	v_pk_fma_f32 v[128:129], v[62:63], v[62:63], v[128:129]
	s_nop 0
	v_add_f32_e32 v128, v128, v129
	s_nop 1
	v_add_f32_dpp v128, v128, v128 quad_perm:[1,0,3,2] row_mask:0xf bank_mask:0xf bound_ctrl:1
	s_nop 1
	v_add_f32_dpp v128, v128, v128 quad_perm:[2,3,0,1] row_mask:0xf bank_mask:0xf bound_ctrl:1
	s_nop 1
	v_add_f32_dpp v128, v128, v128 row_half_mirror row_mask:0xf bank_mask:0xf bound_ctrl:1
	s_nop 1
	v_add_f32_dpp v128, v128, v128 row_mirror row_mask:0xf bank_mask:0xf bound_ctrl:1
	s_nop 1
	v_readlane_b32 s20, v128, 0
	v_readlane_b32 s21, v128, 32
	v_readlane_b32 s22, v128, 16
	v_readlane_b32 s23, v128, 48
	s_nop 1
	v_mov_b32_e32 v130, s22
	v_mov_b32_e32 v131, s23
	v_pk_add_f32 v[130:131], s[20:21], v[130:131]
	s_nop 0
	v_add_f32_e32 v130, v130, v131
	v_fma_f32 v130, v130, v194, v195
	v_rsq_f32_e32 v130, v130
	s_nop 0
	v_pk_mul_f32 v[96:97], v[48:49], v[130:131] op_sel_hi:[1,0]
	v_pk_mul_f32 v[98:99], v[50:51], v[130:131] op_sel_hi:[1,0]
	v_pk_mul_f32 v[100:101], v[52:53], v[130:131] op_sel_hi:[1,0]
	v_pk_mul_f32 v[102:103], v[54:55], v[130:131] op_sel_hi:[1,0]
	v_pk_mul_f32 v[104:105], v[56:57], v[130:131] op_sel_hi:[1,0]
	v_pk_mul_f32 v[106:107], v[58:59], v[130:131] op_sel_hi:[1,0]
	v_pk_mul_f32 v[108:109], v[60:61], v[130:131] op_sel_hi:[1,0]
	v_pk_mul_f32 v[110:111], v[62:63], v[130:131] op_sel_hi:[1,0]
	v_pk_mul_f32 v[96:97], v[0:1], v[96:97]
	v_pk_mul_f32 v[98:99], v[2:3], v[98:99]
	v_pk_mul_f32 v[100:101], v[4:5], v[100:101]
	v_pk_mul_f32 v[102:103], v[6:7], v[102:103]
	v_pk_mul_f32 v[104:105], v[8:9], v[104:105]
	v_pk_mul_f32 v[106:107], v[10:11], v[106:107]
	v_pk_mul_f32 v[108:109], v[12:13], v[108:109]
	v_pk_mul_f32 v[110:111], v[14:15], v[110:111]
	v_cvt_pk_bf16_f32 v170, v96, v97
	v_cvt_pk_bf16_f32 v171, v98, v99
	v_cvt_pk_bf16_f32 v172, v100, v101
	v_cvt_pk_bf16_f32 v173, v102, v103
	v_cvt_pk_bf16_f32 v174, v104, v105
	v_cvt_pk_bf16_f32 v175, v106, v107
	v_cvt_pk_bf16_f32 v176, v108, v109
	v_cvt_pk_bf16_f32 v177, v110, v111
	v_lshlrev_b32_e32 v136, 16, v170
	v_and_b32_e32 v137, 0xffff0000, v170
	v_lshlrev_b32_e32 v138, 16, v171
	v_and_b32_e32 v139, 0xffff0000, v171
	v_lshlrev_b32_e32 v140, 16, v172
	v_and_b32_e32 v141, 0xffff0000, v172
	v_lshlrev_b32_e32 v142, 16, v173
	v_and_b32_e32 v143, 0xffff0000, v173
	v_lshlrev_b32_e32 v144, 16, v174
	v_and_b32_e32 v145, 0xffff0000, v174
	v_lshlrev_b32_e32 v146, 16, v175
	v_and_b32_e32 v147, 0xffff0000, v175
	v_lshlrev_b32_e32 v148, 16, v176
	v_and_b32_e32 v149, 0xffff0000, v176
	v_lshlrev_b32_e32 v150, 16, v177
	v_and_b32_e32 v151, 0xffff0000, v177
	v_pk_add_f32 v[112:113], v[80:81], v[136:137] neg_lo:[0,1] neg_hi:[0,1]
	v_pk_add_f32 v[114:115], v[82:83], v[138:139] neg_lo:[0,1] neg_hi:[0,1]
	v_pk_add_f32 v[116:117], v[84:85], v[140:141] neg_lo:[0,1] neg_hi:[0,1]
	v_pk_add_f32 v[118:119], v[86:87], v[142:143] neg_lo:[0,1] neg_hi:[0,1]
	v_pk_add_f32 v[120:121], v[88:89], v[144:145] neg_lo:[0,1] neg_hi:[0,1]
	v_pk_add_f32 v[122:123], v[90:91], v[146:147] neg_lo:[0,1] neg_hi:[0,1]
	v_pk_add_f32 v[124:125], v[92:93], v[148:149] neg_lo:[0,1] neg_hi:[0,1]
	v_pk_add_f32 v[126:127], v[94:95], v[150:151] neg_lo:[0,1] neg_hi:[0,1]
	global_store_dwordx2 v200, v[170:171], s[10:11]
	global_store_dwordx2 v200, v[172:173], s[10:11] offset:512
	global_store_dwordx2 v200, v[174:175], s[10:11] offset:1024
	global_store_dwordx2 v200, v[176:177], s[10:11] offset:1536
	v_pk_fma_f32 v[96:97], v[112:113], v[16:17], v[136:137]
	v_pk_fma_f32 v[98:99], v[114:115], v[18:19], v[138:139]
	v_pk_fma_f32 v[100:101], v[116:117], v[20:21], v[140:141]
	v_pk_fma_f32 v[102:103], v[118:119], v[22:23], v[142:143]
	v_pk_fma_f32 v[104:105], v[120:121], v[24:25], v[144:145]
	v_pk_fma_f32 v[106:107], v[122:123], v[26:27], v[146:147]
	v_pk_fma_f32 v[108:109], v[124:125], v[28:29], v[148:149]
	v_pk_fma_f32 v[110:111], v[126:127], v[30:31], v[150:151]
	v_cvt_pk_bf16_f32 v178, v96, v97
	v_cvt_pk_bf16_f32 v179, v98, v99
	v_cvt_pk_bf16_f32 v180, v100, v101
	v_cvt_pk_bf16_f32 v181, v102, v103
	v_cvt_pk_bf16_f32 v182, v104, v105
	v_cvt_pk_bf16_f32 v183, v106, v107
	v_cvt_pk_bf16_f32 v184, v108, v109
	v_cvt_pk_bf16_f32 v185, v110, v111
	global_store_dwordx2 v200, v[178:179], s[6:7]
	global_store_dwordx2 v200, v[180:181], s[6:7] offset:512
	global_store_dwordx2 v200, v[182:183], s[6:7] offset:1024
	global_store_dwordx2 v200, v[184:185], s[6:7] offset:1536
	v_pk_fma_f32 v[96:97], v[112:113], v[32:33], v[136:137]
	v_pk_fma_f32 v[98:99], v[114:115], v[34:35], v[138:139]
	v_pk_fma_f32 v[100:101], v[116:117], v[36:37], v[140:141]
	v_pk_fma_f32 v[102:103], v[118:119], v[38:39], v[142:143]
	v_pk_fma_f32 v[104:105], v[120:121], v[40:41], v[144:145]
	v_pk_fma_f32 v[106:107], v[122:123], v[42:43], v[146:147]
	v_pk_fma_f32 v[108:109], v[124:125], v[44:45], v[148:149]
	v_pk_fma_f32 v[110:111], v[126:127], v[46:47], v[150:151]
	v_cvt_pk_bf16_f32 v186, v96, v97
	v_cvt_pk_bf16_f32 v187, v98, v99
	v_cvt_pk_bf16_f32 v188, v100, v101
	v_cvt_pk_bf16_f32 v189, v102, v103
	v_cvt_pk_bf16_f32 v190, v104, v105
	v_cvt_pk_bf16_f32 v191, v106, v107
	v_cvt_pk_bf16_f32 v192, v108, v109
	v_cvt_pk_bf16_f32 v193, v110, v111
	global_store_dwordx2 v200, v[186:187], s[8:9]
	global_store_dwordx2 v200, v[188:189], s[8:9] offset:512
	global_store_dwordx2 v200, v[190:191], s[8:9] offset:1024
	global_store_dwordx2 v200, v[192:193], s[8:9] offset:1536
	v_add_u32_e32 v200, 0x800, v200
	s_waitcnt vmcnt(12)
	global_load_dwordx4 v[48:51], v199, s[12:13]
	global_load_dwordx4 v[52:55], v199, s[12:13] offset:1024
	global_load_dwordx4 v[56:59], v199, s[12:13] offset:2048
	global_load_dwordx4 v[60:63], v199, s[12:13] offset:3072
	v_add_u32_e32 v199, 0x1000, v199
	v_pk_mul_f32 v[128:129], v[64:65], v[64:65]
	v_pk_fma_f32 v[128:129], v[66:67], v[66:67], v[128:129]
	v_pk_fma_f32 v[128:129], v[68:69], v[68:69], v[128:129]
	v_pk_fma_f32 v[128:129], v[70:71], v[70:71], v[128:129]
	v_pk_fma_f32 v[128:129], v[72:73], v[72:73], v[128:129]
	v_pk_fma_f32 v[128:129], v[74:75], v[74:75], v[128:129]
	v_pk_fma_f32 v[128:129], v[76:77], v[76:77], v[128:129]
	v_pk_fma_f32 v[128:129], v[78:79], v[78:79], v[128:129]
	s_nop 0
	v_add_f32_e32 v128, v128, v129
	s_nop 1
	v_add_f32_dpp v128, v128, v128 quad_perm:[1,0,3,2] row_mask:0xf bank_mask:0xf bound_ctrl:1
	s_nop 1
	v_add_f32_dpp v128, v128, v128 quad_perm:[2,3,0,1] row_mask:0xf bank_mask:0xf bound_ctrl:1
	s_nop 1
	v_add_f32_dpp v128, v128, v128 row_half_mirror row_mask:0xf bank_mask:0xf bound_ctrl:1
	s_nop 1
	v_add_f32_dpp v128, v128, v128 row_mirror row_mask:0xf bank_mask:0xf bound_ctrl:1
	s_nop 1
	v_readlane_b32 s20, v128, 0
	v_readlane_b32 s21, v128, 32
	v_readlane_b32 s22, v128, 16
	v_readlane_b32 s23, v128, 48
	s_nop 1
	v_mov_b32_e32 v130, s22
	v_mov_b32_e32 v131, s23
	v_pk_add_f32 v[130:131], s[20:21], v[130:131]
	s_nop 0
	v_add_f32_e32 v130, v130, v131
	v_fma_f32 v130, v130, v194, v195
	v_rsq_f32_e32 v130, v130
	s_nop 0
	v_pk_mul_f32 v[96:97], v[64:65], v[130:131] op_sel_hi:[1,0]
	v_pk_mul_f32 v[98:99], v[66:67], v[130:131] op_sel_hi:[1,0]
	v_pk_mul_f32 v[100:101], v[68:69], v[130:131] op_sel_hi:[1,0]
	v_pk_mul_f32 v[102:103], v[70:71], v[130:131] op_sel_hi:[1,0]
	v_pk_mul_f32 v[104:105], v[72:73], v[130:131] op_sel_hi:[1,0]
	v_pk_mul_f32 v[106:107], v[74:75], v[130:131] op_sel_hi:[1,0]
	v_pk_mul_f32 v[108:109], v[76:77], v[130:131] op_sel_hi:[1,0]
	v_pk_mul_f32 v[110:111], v[78:79], v[130:131] op_sel_hi:[1,0]
	v_pk_mul_f32 v[96:97], v[0:1], v[96:97]
	v_pk_mul_f32 v[98:99], v[2:3], v[98:99]
	v_pk_mul_f32 v[100:101], v[4:5], v[100:101]
	v_pk_mul_f32 v[102:103], v[6:7], v[102:103]
	v_pk_mul_f32 v[104:105], v[8:9], v[104:105]
	v_pk_mul_f32 v[106:107], v[10:11], v[106:107]
	v_pk_mul_f32 v[108:109], v[12:13], v[108:109]
	v_pk_mul_f32 v[110:111], v[14:15], v[110:111]
	v_cvt_pk_bf16_f32 v170, v96, v97
	v_cvt_pk_bf16_f32 v171, v98, v99
	v_cvt_pk_bf16_f32 v172, v100, v101
	v_cvt_pk_bf16_f32 v173, v102, v103
	v_cvt_pk_bf16_f32 v174, v104, v105
	v_cvt_pk_bf16_f32 v175, v106, v107
	v_cvt_pk_bf16_f32 v176, v108, v109
	v_cvt_pk_bf16_f32 v177, v110, v111
	v_lshlrev_b32_e32 v80, 16, v170
	v_and_b32_e32 v81, 0xffff0000, v170
	v_lshlrev_b32_e32 v82, 16, v171
	v_and_b32_e32 v83, 0xffff0000, v171
	v_lshlrev_b32_e32 v84, 16, v172
	v_and_b32_e32 v85, 0xffff0000, v172
	v_lshlrev_b32_e32 v86, 16, v173
	v_and_b32_e32 v87, 0xffff0000, v173
	v_lshlrev_b32_e32 v88, 16, v174
	v_and_b32_e32 v89, 0xffff0000, v174
	v_lshlrev_b32_e32 v90, 16, v175
	v_and_b32_e32 v91, 0xffff0000, v175
	v_lshlrev_b32_e32 v92, 16, v176
	v_and_b32_e32 v93, 0xffff0000, v176
	v_lshlrev_b32_e32 v94, 16, v177
	v_and_b32_e32 v95, 0xffff0000, v177
	v_pk_add_f32 v[112:113], v[136:137], v[80:81] neg_lo:[0,1] neg_hi:[0,1]
	v_pk_add_f32 v[114:115], v[138:139], v[82:83] neg_lo:[0,1] neg_hi:[0,1]
	v_pk_add_f32 v[116:117], v[140:141], v[84:85] neg_lo:[0,1] neg_hi:[0,1]
	v_pk_add_f32 v[118:119], v[142:143], v[86:87] neg_lo:[0,1] neg_hi:[0,1]
	v_pk_add_f32 v[120:121], v[144:145], v[88:89] neg_lo:[0,1] neg_hi:[0,1]
	v_pk_add_f32 v[122:123], v[146:147], v[90:91] neg_lo:[0,1] neg_hi:[0,1]
	v_pk_add_f32 v[124:125], v[148:149], v[92:93] neg_lo:[0,1] neg_hi:[0,1]
	v_pk_add_f32 v[126:127], v[150:151], v[94:95] neg_lo:[0,1] neg_hi:[0,1]
	global_store_dwordx2 v200, v[170:171], s[10:11]
	global_store_dwordx2 v200, v[172:173], s[10:11] offset:512
	global_store_dwordx2 v200, v[174:175], s[10:11] offset:1024
	global_store_dwordx2 v200, v[176:177], s[10:11] offset:1536
	v_pk_fma_f32 v[96:97], v[112:113], v[16:17], v[80:81]
	v_pk_fma_f32 v[98:99], v[114:115], v[18:19], v[82:83]
	v_pk_fma_f32 v[100:101], v[116:117], v[20:21], v[84:85]
	v_pk_fma_f32 v[102:103], v[118:119], v[22:23], v[86:87]
	v_pk_fma_f32 v[104:105], v[120:121], v[24:25], v[88:89]
	v_pk_fma_f32 v[106:107], v[122:123], v[26:27], v[90:91]
	v_pk_fma_f32 v[108:109], v[124:125], v[28:29], v[92:93]
	v_pk_fma_f32 v[110:111], v[126:127], v[30:31], v[94:95]
	v_cvt_pk_bf16_f32 v178, v96, v97
	v_cvt_pk_bf16_f32 v179, v98, v99
	v_cvt_pk_bf16_f32 v180, v100, v101
	v_cvt_pk_bf16_f32 v181, v102, v103
	v_cvt_pk_bf16_f32 v182, v104, v105
	v_cvt_pk_bf16_f32 v183, v106, v107
	v_cvt_pk_bf16_f32 v184, v108, v109
	v_cvt_pk_bf16_f32 v185, v110, v111
	global_store_dwordx2 v200, v[178:179], s[6:7]
	global_store_dwordx2 v200, v[180:181], s[6:7] offset:512
	global_store_dwordx2 v200, v[182:183], s[6:7] offset:1024
	global_store_dwordx2 v200, v[184:185], s[6:7] offset:1536
	v_pk_fma_f32 v[96:97], v[112:113], v[32:33], v[80:81]
	v_pk_fma_f32 v[98:99], v[114:115], v[34:35], v[82:83]
	v_pk_fma_f32 v[100:101], v[116:117], v[36:37], v[84:85]
	v_pk_fma_f32 v[102:103], v[118:119], v[38:39], v[86:87]
	v_pk_fma_f32 v[104:105], v[120:121], v[40:41], v[88:89]
	v_pk_fma_f32 v[106:107], v[122:123], v[42:43], v[90:91]
	v_pk_fma_f32 v[108:109], v[124:125], v[44:45], v[92:93]
	v_pk_fma_f32 v[110:111], v[126:127], v[46:47], v[94:95]
	v_cvt_pk_bf16_f32 v186, v96, v97
	v_cvt_pk_bf16_f32 v187, v98, v99
	v_cvt_pk_bf16_f32 v188, v100, v101
	v_cvt_pk_bf16_f32 v189, v102, v103
	v_cvt_pk_bf16_f32 v190, v104, v105
	v_cvt_pk_bf16_f32 v191, v106, v107
	v_cvt_pk_bf16_f32 v192, v108, v109
	v_cvt_pk_bf16_f32 v193, v110, v111
	global_store_dwordx2 v200, v[186:187], s[8:9]
	global_store_dwordx2 v200, v[188:189], s[8:9] offset:512
	global_store_dwordx2 v200, v[190:191], s[8:9] offset:1024
	global_store_dwordx2 v200, v[192:193], s[8:9] offset:1536
	v_add_u32_e32 v200, 0x800, v200
	s_waitcnt vmcnt(12)
	global_load_dwordx4 v[64:67], v199, s[12:13]
	global_load_dwordx4 v[68:71], v199, s[12:13] offset:1024
	global_load_dwordx4 v[72:75], v199, s[12:13] offset:2048
	global_load_dwordx4 v[76:79], v199, s[12:13] offset:3072
	v_add_u32_e32 v199, 0x1000, v199
	v_pk_mul_f32 v[128:129], v[48:49], v[48:49]
	v_pk_fma_f32 v[128:129], v[50:51], v[50:51], v[128:129]
	v_pk_fma_f32 v[128:129], v[52:53], v[52:53], v[128:129]
	v_pk_fma_f32 v[128:129], v[54:55], v[54:55], v[128:129]
	v_pk_fma_f32 v[128:129], v[56:57], v[56:57], v[128:129]
	v_pk_fma_f32 v[128:129], v[58:59], v[58:59], v[128:129]
	v_pk_fma_f32 v[128:129], v[60:61], v[60:61], v[128:129]
	v_pk_fma_f32 v[128:129], v[62:63], v[62:63], v[128:129]
	s_nop 0
	v_add_f32_e32 v128, v128, v129
	s_nop 1
	v_add_f32_dpp v128, v128, v128 quad_perm:[1,0,3,2] row_mask:0xf bank_mask:0xf bound_ctrl:1
	s_nop 1
	v_add_f32_dpp v128, v128, v128 quad_perm:[2,3,0,1] row_mask:0xf bank_mask:0xf bound_ctrl:1
	s_nop 1
	v_add_f32_dpp v128, v128, v128 row_half_mirror row_mask:0xf bank_mask:0xf bound_ctrl:1
	s_nop 1
	v_add_f32_dpp v128, v128, v128 row_mirror row_mask:0xf bank_mask:0xf bound_ctrl:1
	s_nop 1
	v_readlane_b32 s20, v128, 0
	v_readlane_b32 s21, v128, 32
	v_readlane_b32 s22, v128, 16
	v_readlane_b32 s23, v128, 48
	s_nop 1
	v_mov_b32_e32 v130, s22
	v_mov_b32_e32 v131, s23
	v_pk_add_f32 v[130:131], s[20:21], v[130:131]
	s_nop 0
	v_add_f32_e32 v130, v130, v131
	v_fma_f32 v130, v130, v194, v195
	v_rsq_f32_e32 v130, v130
	s_nop 0
	v_pk_mul_f32 v[96:97], v[48:49], v[130:131] op_sel_hi:[1,0]
	v_pk_mul_f32 v[98:99], v[50:51], v[130:131] op_sel_hi:[1,0]
	v_pk_mul_f32 v[100:101], v[52:53], v[130:131] op_sel_hi:[1,0]
	v_pk_mul_f32 v[102:103], v[54:55], v[130:131] op_sel_hi:[1,0]
	v_pk_mul_f32 v[104:105], v[56:57], v[130:131] op_sel_hi:[1,0]
	v_pk_mul_f32 v[106:107], v[58:59], v[130:131] op_sel_hi:[1,0]
	v_pk_mul_f32 v[108:109], v[60:61], v[130:131] op_sel_hi:[1,0]
	v_pk_mul_f32 v[110:111], v[62:63], v[130:131] op_sel_hi:[1,0]
	v_pk_mul_f32 v[96:97], v[0:1], v[96:97]
	v_pk_mul_f32 v[98:99], v[2:3], v[98:99]
	v_pk_mul_f32 v[100:101], v[4:5], v[100:101]
	v_pk_mul_f32 v[102:103], v[6:7], v[102:103]
	v_pk_mul_f32 v[104:105], v[8:9], v[104:105]
	v_pk_mul_f32 v[106:107], v[10:11], v[106:107]
	v_pk_mul_f32 v[108:109], v[12:13], v[108:109]
	v_pk_mul_f32 v[110:111], v[14:15], v[110:111]
	v_cvt_pk_bf16_f32 v170, v96, v97
	v_cvt_pk_bf16_f32 v171, v98, v99
	v_cvt_pk_bf16_f32 v172, v100, v101
	v_cvt_pk_bf16_f32 v173, v102, v103
	v_cvt_pk_bf16_f32 v174, v104, v105
	v_cvt_pk_bf16_f32 v175, v106, v107
	v_cvt_pk_bf16_f32 v176, v108, v109
	v_cvt_pk_bf16_f32 v177, v110, v111
	v_lshlrev_b32_e32 v136, 16, v170
	v_and_b32_e32 v137, 0xffff0000, v170
	v_lshlrev_b32_e32 v138, 16, v171
	v_and_b32_e32 v139, 0xffff0000, v171
	v_lshlrev_b32_e32 v140, 16, v172
	v_and_b32_e32 v141, 0xffff0000, v172
	v_lshlrev_b32_e32 v142, 16, v173
	v_and_b32_e32 v143, 0xffff0000, v173
	v_lshlrev_b32_e32 v144, 16, v174
	v_and_b32_e32 v145, 0xffff0000, v174
	v_lshlrev_b32_e32 v146, 16, v175
	v_and_b32_e32 v147, 0xffff0000, v175
	v_lshlrev_b32_e32 v148, 16, v176
	v_and_b32_e32 v149, 0xffff0000, v176
	v_lshlrev_b32_e32 v150, 16, v177
	v_and_b32_e32 v151, 0xffff0000, v177
	v_pk_add_f32 v[112:113], v[80:81], v[136:137] neg_lo:[0,1] neg_hi:[0,1]
	v_pk_add_f32 v[114:115], v[82:83], v[138:139] neg_lo:[0,1] neg_hi:[0,1]
	v_pk_add_f32 v[116:117], v[84:85], v[140:141] neg_lo:[0,1] neg_hi:[0,1]
	v_pk_add_f32 v[118:119], v[86:87], v[142:143] neg_lo:[0,1] neg_hi:[0,1]
	v_pk_add_f32 v[120:121], v[88:89], v[144:145] neg_lo:[0,1] neg_hi:[0,1]
	v_pk_add_f32 v[122:123], v[90:91], v[146:147] neg_lo:[0,1] neg_hi:[0,1]
	v_pk_add_f32 v[124:125], v[92:93], v[148:149] neg_lo:[0,1] neg_hi:[0,1]
	v_pk_add_f32 v[126:127], v[94:95], v[150:151] neg_lo:[0,1] neg_hi:[0,1]
	global_store_dwordx2 v200, v[170:171], s[10:11]
	global_store_dwordx2 v200, v[172:173], s[10:11] offset:512
	global_store_dwordx2 v200, v[174:175], s[10:11] offset:1024
	global_store_dwordx2 v200, v[176:177], s[10:11] offset:1536
	v_pk_fma_f32 v[96:97], v[112:113], v[16:17], v[136:137]
	v_pk_fma_f32 v[98:99], v[114:115], v[18:19], v[138:139]
	v_pk_fma_f32 v[100:101], v[116:117], v[20:21], v[140:141]
	v_pk_fma_f32 v[102:103], v[118:119], v[22:23], v[142:143]
	v_pk_fma_f32 v[104:105], v[120:121], v[24:25], v[144:145]
	v_pk_fma_f32 v[106:107], v[122:123], v[26:27], v[146:147]
	v_pk_fma_f32 v[108:109], v[124:125], v[28:29], v[148:149]
	v_pk_fma_f32 v[110:111], v[126:127], v[30:31], v[150:151]
	v_cvt_pk_bf16_f32 v178, v96, v97
	v_cvt_pk_bf16_f32 v179, v98, v99
	v_cvt_pk_bf16_f32 v180, v100, v101
	v_cvt_pk_bf16_f32 v181, v102, v103
	v_cvt_pk_bf16_f32 v182, v104, v105
	v_cvt_pk_bf16_f32 v183, v106, v107
	v_cvt_pk_bf16_f32 v184, v108, v109
	v_cvt_pk_bf16_f32 v185, v110, v111
	global_store_dwordx2 v200, v[178:179], s[6:7]
	global_store_dwordx2 v200, v[180:181], s[6:7] offset:512
	global_store_dwordx2 v200, v[182:183], s[6:7] offset:1024
	global_store_dwordx2 v200, v[184:185], s[6:7] offset:1536
	v_pk_fma_f32 v[96:97], v[112:113], v[32:33], v[136:137]
	v_pk_fma_f32 v[98:99], v[114:115], v[34:35], v[138:139]
	v_pk_fma_f32 v[100:101], v[116:117], v[36:37], v[140:141]
	v_pk_fma_f32 v[102:103], v[118:119], v[38:39], v[142:143]
	v_pk_fma_f32 v[104:105], v[120:121], v[40:41], v[144:145]
	v_pk_fma_f32 v[106:107], v[122:123], v[42:43], v[146:147]
	v_pk_fma_f32 v[108:109], v[124:125], v[44:45], v[148:149]
	v_pk_fma_f32 v[110:111], v[126:127], v[46:47], v[150:151]
	v_cvt_pk_bf16_f32 v186, v96, v97
	v_cvt_pk_bf16_f32 v187, v98, v99
	v_cvt_pk_bf16_f32 v188, v100, v101
	v_cvt_pk_bf16_f32 v189, v102, v103
	v_cvt_pk_bf16_f32 v190, v104, v105
	v_cvt_pk_bf16_f32 v191, v106, v107
	v_cvt_pk_bf16_f32 v192, v108, v109
	v_cvt_pk_bf16_f32 v193, v110, v111
	global_store_dwordx2 v200, v[186:187], s[8:9]
	global_store_dwordx2 v200, v[188:189], s[8:9] offset:512
	global_store_dwordx2 v200, v[190:191], s[8:9] offset:1024
	global_store_dwordx2 v200, v[192:193], s[8:9] offset:1536
	v_add_u32_e32 v200, 0x800, v200
	s_waitcnt vmcnt(12)
	global_load_dwordx4 v[48:51], v199, s[12:13]
	global_load_dwordx4 v[52:55], v199, s[12:13] offset:1024
	global_load_dwordx4 v[56:59], v199, s[12:13] offset:2048
	global_load_dwordx4 v[60:63], v199, s[12:13] offset:3072
	v_add_u32_e32 v199, 0x1000, v199
	v_pk_mul_f32 v[128:129], v[64:65], v[64:65]
	v_pk_fma_f32 v[128:129], v[66:67], v[66:67], v[128:129]
	v_pk_fma_f32 v[128:129], v[68:69], v[68:69], v[128:129]
	v_pk_fma_f32 v[128:129], v[70:71], v[70:71], v[128:129]
	v_pk_fma_f32 v[128:129], v[72:73], v[72:73], v[128:129]
	v_pk_fma_f32 v[128:129], v[74:75], v[74:75], v[128:129]
	v_pk_fma_f32 v[128:129], v[76:77], v[76:77], v[128:129]
	v_pk_fma_f32 v[128:129], v[78:79], v[78:79], v[128:129]
	s_nop 0
	v_add_f32_e32 v128, v128, v129
	s_nop 1
	v_add_f32_dpp v128, v128, v128 quad_perm:[1,0,3,2] row_mask:0xf bank_mask:0xf bound_ctrl:1
	s_nop 1
	v_add_f32_dpp v128, v128, v128 quad_perm:[2,3,0,1] row_mask:0xf bank_mask:0xf bound_ctrl:1
	s_nop 1
	v_add_f32_dpp v128, v128, v128 row_half_mirror row_mask:0xf bank_mask:0xf bound_ctrl:1
	s_nop 1
	v_add_f32_dpp v128, v128, v128 row_mirror row_mask:0xf bank_mask:0xf bound_ctrl:1
	s_nop 1
	v_readlane_b32 s20, v128, 0
	v_readlane_b32 s21, v128, 32
	v_readlane_b32 s22, v128, 16
	v_readlane_b32 s23, v128, 48
	s_nop 1
	v_mov_b32_e32 v130, s22
	v_mov_b32_e32 v131, s23
	v_pk_add_f32 v[130:131], s[20:21], v[130:131]
	s_nop 0
	v_add_f32_e32 v130, v130, v131
	v_fma_f32 v130, v130, v194, v195
	v_rsq_f32_e32 v130, v130
	s_nop 0
	v_pk_mul_f32 v[96:97], v[64:65], v[130:131] op_sel_hi:[1,0]
	v_pk_mul_f32 v[98:99], v[66:67], v[130:131] op_sel_hi:[1,0]
	v_pk_mul_f32 v[100:101], v[68:69], v[130:131] op_sel_hi:[1,0]
	v_pk_mul_f32 v[102:103], v[70:71], v[130:131] op_sel_hi:[1,0]
	v_pk_mul_f32 v[104:105], v[72:73], v[130:131] op_sel_hi:[1,0]
	v_pk_mul_f32 v[106:107], v[74:75], v[130:131] op_sel_hi:[1,0]
	v_pk_mul_f32 v[108:109], v[76:77], v[130:131] op_sel_hi:[1,0]
	v_pk_mul_f32 v[110:111], v[78:79], v[130:131] op_sel_hi:[1,0]
	v_pk_mul_f32 v[96:97], v[0:1], v[96:97]
	v_pk_mul_f32 v[98:99], v[2:3], v[98:99]
	v_pk_mul_f32 v[100:101], v[4:5], v[100:101]
	v_pk_mul_f32 v[102:103], v[6:7], v[102:103]
	v_pk_mul_f32 v[104:105], v[8:9], v[104:105]
	v_pk_mul_f32 v[106:107], v[10:11], v[106:107]
	v_pk_mul_f32 v[108:109], v[12:13], v[108:109]
	v_pk_mul_f32 v[110:111], v[14:15], v[110:111]
	v_cvt_pk_bf16_f32 v170, v96, v97
	v_cvt_pk_bf16_f32 v171, v98, v99
	v_cvt_pk_bf16_f32 v172, v100, v101
	v_cvt_pk_bf16_f32 v173, v102, v103
	v_cvt_pk_bf16_f32 v174, v104, v105
	v_cvt_pk_bf16_f32 v175, v106, v107
	v_cvt_pk_bf16_f32 v176, v108, v109
	v_cvt_pk_bf16_f32 v177, v110, v111
	v_lshlrev_b32_e32 v80, 16, v170
	v_and_b32_e32 v81, 0xffff0000, v170
	v_lshlrev_b32_e32 v82, 16, v171
	v_and_b32_e32 v83, 0xffff0000, v171
	v_lshlrev_b32_e32 v84, 16, v172
	v_and_b32_e32 v85, 0xffff0000, v172
	v_lshlrev_b32_e32 v86, 16, v173
	v_and_b32_e32 v87, 0xffff0000, v173
	v_lshlrev_b32_e32 v88, 16, v174
	v_and_b32_e32 v89, 0xffff0000, v174
	v_lshlrev_b32_e32 v90, 16, v175
	v_and_b32_e32 v91, 0xffff0000, v175
	v_lshlrev_b32_e32 v92, 16, v176
	v_and_b32_e32 v93, 0xffff0000, v176
	v_lshlrev_b32_e32 v94, 16, v177
	v_and_b32_e32 v95, 0xffff0000, v177
	v_pk_add_f32 v[112:113], v[136:137], v[80:81] neg_lo:[0,1] neg_hi:[0,1]
	v_pk_add_f32 v[114:115], v[138:139], v[82:83] neg_lo:[0,1] neg_hi:[0,1]
	v_pk_add_f32 v[116:117], v[140:141], v[84:85] neg_lo:[0,1] neg_hi:[0,1]
	v_pk_add_f32 v[118:119], v[142:143], v[86:87] neg_lo:[0,1] neg_hi:[0,1]
	v_pk_add_f32 v[120:121], v[144:145], v[88:89] neg_lo:[0,1] neg_hi:[0,1]
	v_pk_add_f32 v[122:123], v[146:147], v[90:91] neg_lo:[0,1] neg_hi:[0,1]
	v_pk_add_f32 v[124:125], v[148:149], v[92:93] neg_lo:[0,1] neg_hi:[0,1]
	v_pk_add_f32 v[126:127], v[150:151], v[94:95] neg_lo:[0,1] neg_hi:[0,1]
	global_store_dwordx2 v200, v[170:171], s[10:11]
	global_store_dwordx2 v200, v[172:173], s[10:11] offset:512
	global_store_dwordx2 v200, v[174:175], s[10:11] offset:1024
	global_store_dwordx2 v200, v[176:177], s[10:11] offset:1536
	v_pk_fma_f32 v[96:97], v[112:113], v[16:17], v[80:81]
	v_pk_fma_f32 v[98:99], v[114:115], v[18:19], v[82:83]
	v_pk_fma_f32 v[100:101], v[116:117], v[20:21], v[84:85]
	v_pk_fma_f32 v[102:103], v[118:119], v[22:23], v[86:87]
	v_pk_fma_f32 v[104:105], v[120:121], v[24:25], v[88:89]
	v_pk_fma_f32 v[106:107], v[122:123], v[26:27], v[90:91]
	v_pk_fma_f32 v[108:109], v[124:125], v[28:29], v[92:93]
	v_pk_fma_f32 v[110:111], v[126:127], v[30:31], v[94:95]
	v_cvt_pk_bf16_f32 v178, v96, v97
	v_cvt_pk_bf16_f32 v179, v98, v99
	v_cvt_pk_bf16_f32 v180, v100, v101
	v_cvt_pk_bf16_f32 v181, v102, v103
	v_cvt_pk_bf16_f32 v182, v104, v105
	v_cvt_pk_bf16_f32 v183, v106, v107
	v_cvt_pk_bf16_f32 v184, v108, v109
	v_cvt_pk_bf16_f32 v185, v110, v111
	global_store_dwordx2 v200, v[178:179], s[6:7]
	global_store_dwordx2 v200, v[180:181], s[6:7] offset:512
	global_store_dwordx2 v200, v[182:183], s[6:7] offset:1024
	global_store_dwordx2 v200, v[184:185], s[6:7] offset:1536
	v_pk_fma_f32 v[96:97], v[112:113], v[32:33], v[80:81]
	v_pk_fma_f32 v[98:99], v[114:115], v[34:35], v[82:83]
	v_pk_fma_f32 v[100:101], v[116:117], v[36:37], v[84:85]
	v_pk_fma_f32 v[102:103], v[118:119], v[38:39], v[86:87]
	v_pk_fma_f32 v[104:105], v[120:121], v[40:41], v[88:89]
	v_pk_fma_f32 v[106:107], v[122:123], v[42:43], v[90:91]
	v_pk_fma_f32 v[108:109], v[124:125], v[44:45], v[92:93]
	v_pk_fma_f32 v[110:111], v[126:127], v[46:47], v[94:95]
	v_cvt_pk_bf16_f32 v186, v96, v97
	v_cvt_pk_bf16_f32 v187, v98, v99
	v_cvt_pk_bf16_f32 v188, v100, v101
	v_cvt_pk_bf16_f32 v189, v102, v103
	v_cvt_pk_bf16_f32 v190, v104, v105
	v_cvt_pk_bf16_f32 v191, v106, v107
	v_cvt_pk_bf16_f32 v192, v108, v109
	v_cvt_pk_bf16_f32 v193, v110, v111
	global_store_dwordx2 v200, v[186:187], s[8:9]
	global_store_dwordx2 v200, v[188:189], s[8:9] offset:512
	global_store_dwordx2 v200, v[190:191], s[8:9] offset:1024
	global_store_dwordx2 v200, v[192:193], s[8:9] offset:1536
	v_add_u32_e32 v200, 0x800, v200
	s_waitcnt vmcnt(12)
	global_load_dwordx4 v[64:67], v199, s[12:13]
	global_load_dwordx4 v[68:71], v199, s[12:13] offset:1024
	global_load_dwordx4 v[72:75], v199, s[12:13] offset:2048
	global_load_dwordx4 v[76:79], v199, s[12:13] offset:3072
	v_add_u32_e32 v199, 0x1000, v199
	v_pk_mul_f32 v[128:129], v[48:49], v[48:49]
	v_pk_fma_f32 v[128:129], v[50:51], v[50:51], v[128:129]
	v_pk_fma_f32 v[128:129], v[52:53], v[52:53], v[128:129]
	v_pk_fma_f32 v[128:129], v[54:55], v[54:55], v[128:129]
	v_pk_fma_f32 v[128:129], v[56:57], v[56:57], v[128:129]
	v_pk_fma_f32 v[128:129], v[58:59], v[58:59], v[128:129]
	v_pk_fma_f32 v[128:129], v[60:61], v[60:61], v[128:129]
	v_pk_fma_f32 v[128:129], v[62:63], v[62:63], v[128:129]
	s_nop 0
	v_add_f32_e32 v128, v128, v129
	s_nop 1
	v_add_f32_dpp v128, v128, v128 quad_perm:[1,0,3,2] row_mask:0xf bank_mask:0xf bound_ctrl:1
	s_nop 1
	v_add_f32_dpp v128, v128, v128 quad_perm:[2,3,0,1] row_mask:0xf bank_mask:0xf bound_ctrl:1
	s_nop 1
	v_add_f32_dpp v128, v128, v128 row_half_mirror row_mask:0xf bank_mask:0xf bound_ctrl:1
	s_nop 1
	v_add_f32_dpp v128, v128, v128 row_mirror row_mask:0xf bank_mask:0xf bound_ctrl:1
	s_nop 1
	v_readlane_b32 s20, v128, 0
	v_readlane_b32 s21, v128, 32
	v_readlane_b32 s22, v128, 16
	v_readlane_b32 s23, v128, 48
	s_nop 1
	v_mov_b32_e32 v130, s22
	v_mov_b32_e32 v131, s23
	v_pk_add_f32 v[130:131], s[20:21], v[130:131]
	s_nop 0
	v_add_f32_e32 v130, v130, v131
	v_fma_f32 v130, v130, v194, v195
	v_rsq_f32_e32 v130, v130
	s_nop 0
	v_pk_mul_f32 v[96:97], v[48:49], v[130:131] op_sel_hi:[1,0]
	v_pk_mul_f32 v[98:99], v[50:51], v[130:131] op_sel_hi:[1,0]
	v_pk_mul_f32 v[100:101], v[52:53], v[130:131] op_sel_hi:[1,0]
	v_pk_mul_f32 v[102:103], v[54:55], v[130:131] op_sel_hi:[1,0]
	v_pk_mul_f32 v[104:105], v[56:57], v[130:131] op_sel_hi:[1,0]
	v_pk_mul_f32 v[106:107], v[58:59], v[130:131] op_sel_hi:[1,0]
	v_pk_mul_f32 v[108:109], v[60:61], v[130:131] op_sel_hi:[1,0]
	v_pk_mul_f32 v[110:111], v[62:63], v[130:131] op_sel_hi:[1,0]
	v_pk_mul_f32 v[96:97], v[0:1], v[96:97]
	v_pk_mul_f32 v[98:99], v[2:3], v[98:99]
	v_pk_mul_f32 v[100:101], v[4:5], v[100:101]
	v_pk_mul_f32 v[102:103], v[6:7], v[102:103]
	v_pk_mul_f32 v[104:105], v[8:9], v[104:105]
	v_pk_mul_f32 v[106:107], v[10:11], v[106:107]
	v_pk_mul_f32 v[108:109], v[12:13], v[108:109]
	v_pk_mul_f32 v[110:111], v[14:15], v[110:111]
	v_cvt_pk_bf16_f32 v170, v96, v97
	v_cvt_pk_bf16_f32 v171, v98, v99
	v_cvt_pk_bf16_f32 v172, v100, v101
	v_cvt_pk_bf16_f32 v173, v102, v103
	v_cvt_pk_bf16_f32 v174, v104, v105
	v_cvt_pk_bf16_f32 v175, v106, v107
	v_cvt_pk_bf16_f32 v176, v108, v109
	v_cvt_pk_bf16_f32 v177, v110, v111
	v_lshlrev_b32_e32 v136, 16, v170
	v_and_b32_e32 v137, 0xffff0000, v170
	v_lshlrev_b32_e32 v138, 16, v171
	v_and_b32_e32 v139, 0xffff0000, v171
	v_lshlrev_b32_e32 v140, 16, v172
	v_and_b32_e32 v141, 0xffff0000, v172
	v_lshlrev_b32_e32 v142, 16, v173
	v_and_b32_e32 v143, 0xffff0000, v173
	v_lshlrev_b32_e32 v144, 16, v174
	v_and_b32_e32 v145, 0xffff0000, v174
	v_lshlrev_b32_e32 v146, 16, v175
	v_and_b32_e32 v147, 0xffff0000, v175
	v_lshlrev_b32_e32 v148, 16, v176
	v_and_b32_e32 v149, 0xffff0000, v176
	v_lshlrev_b32_e32 v150, 16, v177
	v_and_b32_e32 v151, 0xffff0000, v177
	v_pk_add_f32 v[112:113], v[80:81], v[136:137] neg_lo:[0,1] neg_hi:[0,1]
	v_pk_add_f32 v[114:115], v[82:83], v[138:139] neg_lo:[0,1] neg_hi:[0,1]
	v_pk_add_f32 v[116:117], v[84:85], v[140:141] neg_lo:[0,1] neg_hi:[0,1]
	v_pk_add_f32 v[118:119], v[86:87], v[142:143] neg_lo:[0,1] neg_hi:[0,1]
	v_pk_add_f32 v[120:121], v[88:89], v[144:145] neg_lo:[0,1] neg_hi:[0,1]
	v_pk_add_f32 v[122:123], v[90:91], v[146:147] neg_lo:[0,1] neg_hi:[0,1]
	v_pk_add_f32 v[124:125], v[92:93], v[148:149] neg_lo:[0,1] neg_hi:[0,1]
	v_pk_add_f32 v[126:127], v[94:95], v[150:151] neg_lo:[0,1] neg_hi:[0,1]
	global_store_dwordx2 v200, v[170:171], s[10:11]
	global_store_dwordx2 v200, v[172:173], s[10:11] offset:512
	global_store_dwordx2 v200, v[174:175], s[10:11] offset:1024
	global_store_dwordx2 v200, v[176:177], s[10:11] offset:1536
	v_pk_fma_f32 v[96:97], v[112:113], v[16:17], v[136:137]
	v_pk_fma_f32 v[98:99], v[114:115], v[18:19], v[138:139]
	v_pk_fma_f32 v[100:101], v[116:117], v[20:21], v[140:141]
	v_pk_fma_f32 v[102:103], v[118:119], v[22:23], v[142:143]
	v_pk_fma_f32 v[104:105], v[120:121], v[24:25], v[144:145]
	v_pk_fma_f32 v[106:107], v[122:123], v[26:27], v[146:147]
	v_pk_fma_f32 v[108:109], v[124:125], v[28:29], v[148:149]
	v_pk_fma_f32 v[110:111], v[126:127], v[30:31], v[150:151]
	v_cvt_pk_bf16_f32 v178, v96, v97
	v_cvt_pk_bf16_f32 v179, v98, v99
	v_cvt_pk_bf16_f32 v180, v100, v101
	v_cvt_pk_bf16_f32 v181, v102, v103
	v_cvt_pk_bf16_f32 v182, v104, v105
	v_cvt_pk_bf16_f32 v183, v106, v107
	v_cvt_pk_bf16_f32 v184, v108, v109
	v_cvt_pk_bf16_f32 v185, v110, v111
	global_store_dwordx2 v200, v[178:179], s[6:7]
	global_store_dwordx2 v200, v[180:181], s[6:7] offset:512
	global_store_dwordx2 v200, v[182:183], s[6:7] offset:1024
	global_store_dwordx2 v200, v[184:185], s[6:7] offset:1536
	v_pk_fma_f32 v[96:97], v[112:113], v[32:33], v[136:137]
	v_pk_fma_f32 v[98:99], v[114:115], v[34:35], v[138:139]
	v_pk_fma_f32 v[100:101], v[116:117], v[36:37], v[140:141]
	v_pk_fma_f32 v[102:103], v[118:119], v[38:39], v[142:143]
	v_pk_fma_f32 v[104:105], v[120:121], v[40:41], v[144:145]
	v_pk_fma_f32 v[106:107], v[122:123], v[42:43], v[146:147]
	v_pk_fma_f32 v[108:109], v[124:125], v[44:45], v[148:149]
	v_pk_fma_f32 v[110:111], v[126:127], v[46:47], v[150:151]
	v_cvt_pk_bf16_f32 v186, v96, v97
	v_cvt_pk_bf16_f32 v187, v98, v99
	v_cvt_pk_bf16_f32 v188, v100, v101
	v_cvt_pk_bf16_f32 v189, v102, v103
	v_cvt_pk_bf16_f32 v190, v104, v105
	v_cvt_pk_bf16_f32 v191, v106, v107
	v_cvt_pk_bf16_f32 v192, v108, v109
	v_cvt_pk_bf16_f32 v193, v110, v111
	global_store_dwordx2 v200, v[186:187], s[8:9]
	global_store_dwordx2 v200, v[188:189], s[8:9] offset:512
	global_store_dwordx2 v200, v[190:191], s[8:9] offset:1024
	global_store_dwordx2 v200, v[192:193], s[8:9] offset:1536
	v_add_u32_e32 v200, 0x800, v200
	s_waitcnt vmcnt(12)
	global_load_dwordx4 v[48:51], v199, s[12:13]
	global_load_dwordx4 v[52:55], v199, s[12:13] offset:1024
	global_load_dwordx4 v[56:59], v199, s[12:13] offset:2048
	global_load_dwordx4 v[60:63], v199, s[12:13] offset:3072
	v_add_u32_e32 v199, 0x1000, v199
	v_pk_mul_f32 v[128:129], v[64:65], v[64:65]
	v_pk_fma_f32 v[128:129], v[66:67], v[66:67], v[128:129]
	v_pk_fma_f32 v[128:129], v[68:69], v[68:69], v[128:129]
	v_pk_fma_f32 v[128:129], v[70:71], v[70:71], v[128:129]
	v_pk_fma_f32 v[128:129], v[72:73], v[72:73], v[128:129]
	v_pk_fma_f32 v[128:129], v[74:75], v[74:75], v[128:129]
	v_pk_fma_f32 v[128:129], v[76:77], v[76:77], v[128:129]
	v_pk_fma_f32 v[128:129], v[78:79], v[78:79], v[128:129]
	s_nop 0
	v_add_f32_e32 v128, v128, v129
	s_nop 1
	v_add_f32_dpp v128, v128, v128 quad_perm:[1,0,3,2] row_mask:0xf bank_mask:0xf bound_ctrl:1
	s_nop 1
	v_add_f32_dpp v128, v128, v128 quad_perm:[2,3,0,1] row_mask:0xf bank_mask:0xf bound_ctrl:1
	s_nop 1
	v_add_f32_dpp v128, v128, v128 row_half_mirror row_mask:0xf bank_mask:0xf bound_ctrl:1
	s_nop 1
	v_add_f32_dpp v128, v128, v128 row_mirror row_mask:0xf bank_mask:0xf bound_ctrl:1
	s_nop 1
	v_readlane_b32 s20, v128, 0
	v_readlane_b32 s21, v128, 32
	v_readlane_b32 s22, v128, 16
	v_readlane_b32 s23, v128, 48
	s_nop 1
	v_mov_b32_e32 v130, s22
	v_mov_b32_e32 v131, s23
	v_pk_add_f32 v[130:131], s[20:21], v[130:131]
	s_nop 0
	v_add_f32_e32 v130, v130, v131
	v_fma_f32 v130, v130, v194, v195
	v_rsq_f32_e32 v130, v130
	s_nop 0
	v_pk_mul_f32 v[96:97], v[64:65], v[130:131] op_sel_hi:[1,0]
	v_pk_mul_f32 v[98:99], v[66:67], v[130:131] op_sel_hi:[1,0]
	v_pk_mul_f32 v[100:101], v[68:69], v[130:131] op_sel_hi:[1,0]
	v_pk_mul_f32 v[102:103], v[70:71], v[130:131] op_sel_hi:[1,0]
	v_pk_mul_f32 v[104:105], v[72:73], v[130:131] op_sel_hi:[1,0]
	v_pk_mul_f32 v[106:107], v[74:75], v[130:131] op_sel_hi:[1,0]
	v_pk_mul_f32 v[108:109], v[76:77], v[130:131] op_sel_hi:[1,0]
	v_pk_mul_f32 v[110:111], v[78:79], v[130:131] op_sel_hi:[1,0]
	v_pk_mul_f32 v[96:97], v[0:1], v[96:97]
	v_pk_mul_f32 v[98:99], v[2:3], v[98:99]
	v_pk_mul_f32 v[100:101], v[4:5], v[100:101]
	v_pk_mul_f32 v[102:103], v[6:7], v[102:103]
	v_pk_mul_f32 v[104:105], v[8:9], v[104:105]
	v_pk_mul_f32 v[106:107], v[10:11], v[106:107]
	v_pk_mul_f32 v[108:109], v[12:13], v[108:109]
	v_pk_mul_f32 v[110:111], v[14:15], v[110:111]
	v_cvt_pk_bf16_f32 v170, v96, v97
	v_cvt_pk_bf16_f32 v171, v98, v99
	v_cvt_pk_bf16_f32 v172, v100, v101
	v_cvt_pk_bf16_f32 v173, v102, v103
	v_cvt_pk_bf16_f32 v174, v104, v105
	v_cvt_pk_bf16_f32 v175, v106, v107
	v_cvt_pk_bf16_f32 v176, v108, v109
	v_cvt_pk_bf16_f32 v177, v110, v111
	v_lshlrev_b32_e32 v80, 16, v170
	v_and_b32_e32 v81, 0xffff0000, v170
	v_lshlrev_b32_e32 v82, 16, v171
	v_and_b32_e32 v83, 0xffff0000, v171
	v_lshlrev_b32_e32 v84, 16, v172
	v_and_b32_e32 v85, 0xffff0000, v172
	v_lshlrev_b32_e32 v86, 16, v173
	v_and_b32_e32 v87, 0xffff0000, v173
	v_lshlrev_b32_e32 v88, 16, v174
	v_and_b32_e32 v89, 0xffff0000, v174
	v_lshlrev_b32_e32 v90, 16, v175
	v_and_b32_e32 v91, 0xffff0000, v175
	v_lshlrev_b32_e32 v92, 16, v176
	v_and_b32_e32 v93, 0xffff0000, v176
	v_lshlrev_b32_e32 v94, 16, v177
	v_and_b32_e32 v95, 0xffff0000, v177
	v_pk_add_f32 v[112:113], v[136:137], v[80:81] neg_lo:[0,1] neg_hi:[0,1]
	v_pk_add_f32 v[114:115], v[138:139], v[82:83] neg_lo:[0,1] neg_hi:[0,1]
	v_pk_add_f32 v[116:117], v[140:141], v[84:85] neg_lo:[0,1] neg_hi:[0,1]
	v_pk_add_f32 v[118:119], v[142:143], v[86:87] neg_lo:[0,1] neg_hi:[0,1]
	v_pk_add_f32 v[120:121], v[144:145], v[88:89] neg_lo:[0,1] neg_hi:[0,1]
	v_pk_add_f32 v[122:123], v[146:147], v[90:91] neg_lo:[0,1] neg_hi:[0,1]
	v_pk_add_f32 v[124:125], v[148:149], v[92:93] neg_lo:[0,1] neg_hi:[0,1]
	v_pk_add_f32 v[126:127], v[150:151], v[94:95] neg_lo:[0,1] neg_hi:[0,1]
	global_store_dwordx2 v200, v[170:171], s[10:11]
	global_store_dwordx2 v200, v[172:173], s[10:11] offset:512
	global_store_dwordx2 v200, v[174:175], s[10:11] offset:1024
	global_store_dwordx2 v200, v[176:177], s[10:11] offset:1536
	v_pk_fma_f32 v[96:97], v[112:113], v[16:17], v[80:81]
	v_pk_fma_f32 v[98:99], v[114:115], v[18:19], v[82:83]
	v_pk_fma_f32 v[100:101], v[116:117], v[20:21], v[84:85]
	v_pk_fma_f32 v[102:103], v[118:119], v[22:23], v[86:87]
	v_pk_fma_f32 v[104:105], v[120:121], v[24:25], v[88:89]
	v_pk_fma_f32 v[106:107], v[122:123], v[26:27], v[90:91]
	v_pk_fma_f32 v[108:109], v[124:125], v[28:29], v[92:93]
	v_pk_fma_f32 v[110:111], v[126:127], v[30:31], v[94:95]
	v_cvt_pk_bf16_f32 v178, v96, v97
	v_cvt_pk_bf16_f32 v179, v98, v99
	v_cvt_pk_bf16_f32 v180, v100, v101
	v_cvt_pk_bf16_f32 v181, v102, v103
	v_cvt_pk_bf16_f32 v182, v104, v105
	v_cvt_pk_bf16_f32 v183, v106, v107
	v_cvt_pk_bf16_f32 v184, v108, v109
	v_cvt_pk_bf16_f32 v185, v110, v111
	global_store_dwordx2 v200, v[178:179], s[6:7]
	global_store_dwordx2 v200, v[180:181], s[6:7] offset:512
	global_store_dwordx2 v200, v[182:183], s[6:7] offset:1024
	global_store_dwordx2 v200, v[184:185], s[6:7] offset:1536
	v_pk_fma_f32 v[96:97], v[112:113], v[32:33], v[80:81]
	v_pk_fma_f32 v[98:99], v[114:115], v[34:35], v[82:83]
	v_pk_fma_f32 v[100:101], v[116:117], v[36:37], v[84:85]
	v_pk_fma_f32 v[102:103], v[118:119], v[38:39], v[86:87]
	v_pk_fma_f32 v[104:105], v[120:121], v[40:41], v[88:89]
	v_pk_fma_f32 v[106:107], v[122:123], v[42:43], v[90:91]
	v_pk_fma_f32 v[108:109], v[124:125], v[44:45], v[92:93]
	v_pk_fma_f32 v[110:111], v[126:127], v[46:47], v[94:95]
	v_cvt_pk_bf16_f32 v186, v96, v97
	v_cvt_pk_bf16_f32 v187, v98, v99
	v_cvt_pk_bf16_f32 v188, v100, v101
	v_cvt_pk_bf16_f32 v189, v102, v103
	v_cvt_pk_bf16_f32 v190, v104, v105
	v_cvt_pk_bf16_f32 v191, v106, v107
	v_cvt_pk_bf16_f32 v192, v108, v109
	v_cvt_pk_bf16_f32 v193, v110, v111
	global_store_dwordx2 v200, v[186:187], s[8:9]
	global_store_dwordx2 v200, v[188:189], s[8:9] offset:512
	global_store_dwordx2 v200, v[190:191], s[8:9] offset:1024
	global_store_dwordx2 v200, v[192:193], s[8:9] offset:1536
	v_add_u32_e32 v200, 0x800, v200
	s_waitcnt vmcnt(12)
	global_load_dwordx4 v[64:67], v199, s[12:13]
	global_load_dwordx4 v[68:71], v199, s[12:13] offset:1024
	global_load_dwordx4 v[72:75], v199, s[12:13] offset:2048
	global_load_dwordx4 v[76:79], v199, s[12:13] offset:3072
	v_add_u32_e32 v199, 0x1000, v199
	v_pk_mul_f32 v[128:129], v[48:49], v[48:49]
	v_pk_fma_f32 v[128:129], v[50:51], v[50:51], v[128:129]
	v_pk_fma_f32 v[128:129], v[52:53], v[52:53], v[128:129]
	v_pk_fma_f32 v[128:129], v[54:55], v[54:55], v[128:129]
	v_pk_fma_f32 v[128:129], v[56:57], v[56:57], v[128:129]
	v_pk_fma_f32 v[128:129], v[58:59], v[58:59], v[128:129]
	v_pk_fma_f32 v[128:129], v[60:61], v[60:61], v[128:129]
	v_pk_fma_f32 v[128:129], v[62:63], v[62:63], v[128:129]
	s_nop 0
	v_add_f32_e32 v128, v128, v129
	s_nop 1
	v_add_f32_dpp v128, v128, v128 quad_perm:[1,0,3,2] row_mask:0xf bank_mask:0xf bound_ctrl:1
	s_nop 1
	v_add_f32_dpp v128, v128, v128 quad_perm:[2,3,0,1] row_mask:0xf bank_mask:0xf bound_ctrl:1
	s_nop 1
	v_add_f32_dpp v128, v128, v128 row_half_mirror row_mask:0xf bank_mask:0xf bound_ctrl:1
	s_nop 1
	v_add_f32_dpp v128, v128, v128 row_mirror row_mask:0xf bank_mask:0xf bound_ctrl:1
	s_nop 1
	v_readlane_b32 s20, v128, 0
	v_readlane_b32 s21, v128, 32
	v_readlane_b32 s22, v128, 16
	v_readlane_b32 s23, v128, 48
	s_nop 1
	v_mov_b32_e32 v130, s22
	v_mov_b32_e32 v131, s23
	v_pk_add_f32 v[130:131], s[20:21], v[130:131]
	s_nop 0
	v_add_f32_e32 v130, v130, v131
	v_fma_f32 v130, v130, v194, v195
	v_rsq_f32_e32 v130, v130
	s_nop 0
	v_pk_mul_f32 v[96:97], v[48:49], v[130:131] op_sel_hi:[1,0]
	v_pk_mul_f32 v[98:99], v[50:51], v[130:131] op_sel_hi:[1,0]
	v_pk_mul_f32 v[100:101], v[52:53], v[130:131] op_sel_hi:[1,0]
	v_pk_mul_f32 v[102:103], v[54:55], v[130:131] op_sel_hi:[1,0]
	v_pk_mul_f32 v[104:105], v[56:57], v[130:131] op_sel_hi:[1,0]
	v_pk_mul_f32 v[106:107], v[58:59], v[130:131] op_sel_hi:[1,0]
	v_pk_mul_f32 v[108:109], v[60:61], v[130:131] op_sel_hi:[1,0]
	v_pk_mul_f32 v[110:111], v[62:63], v[130:131] op_sel_hi:[1,0]
	v_pk_mul_f32 v[96:97], v[0:1], v[96:97]
	v_pk_mul_f32 v[98:99], v[2:3], v[98:99]
	v_pk_mul_f32 v[100:101], v[4:5], v[100:101]
	v_pk_mul_f32 v[102:103], v[6:7], v[102:103]
	v_pk_mul_f32 v[104:105], v[8:9], v[104:105]
	v_pk_mul_f32 v[106:107], v[10:11], v[106:107]
	v_pk_mul_f32 v[108:109], v[12:13], v[108:109]
	v_pk_mul_f32 v[110:111], v[14:15], v[110:111]
	v_cvt_pk_bf16_f32 v170, v96, v97
	v_cvt_pk_bf16_f32 v171, v98, v99
	v_cvt_pk_bf16_f32 v172, v100, v101
	v_cvt_pk_bf16_f32 v173, v102, v103
	v_cvt_pk_bf16_f32 v174, v104, v105
	v_cvt_pk_bf16_f32 v175, v106, v107
	v_cvt_pk_bf16_f32 v176, v108, v109
	v_cvt_pk_bf16_f32 v177, v110, v111
	v_lshlrev_b32_e32 v136, 16, v170
	v_and_b32_e32 v137, 0xffff0000, v170
	v_lshlrev_b32_e32 v138, 16, v171
	v_and_b32_e32 v139, 0xffff0000, v171
	v_lshlrev_b32_e32 v140, 16, v172
	v_and_b32_e32 v141, 0xffff0000, v172
	v_lshlrev_b32_e32 v142, 16, v173
	v_and_b32_e32 v143, 0xffff0000, v173
	v_lshlrev_b32_e32 v144, 16, v174
	v_and_b32_e32 v145, 0xffff0000, v174
	v_lshlrev_b32_e32 v146, 16, v175
	v_and_b32_e32 v147, 0xffff0000, v175
	v_lshlrev_b32_e32 v148, 16, v176
	v_and_b32_e32 v149, 0xffff0000, v176
	v_lshlrev_b32_e32 v150, 16, v177
	v_and_b32_e32 v151, 0xffff0000, v177
	v_pk_add_f32 v[112:113], v[80:81], v[136:137] neg_lo:[0,1] neg_hi:[0,1]
	v_pk_add_f32 v[114:115], v[82:83], v[138:139] neg_lo:[0,1] neg_hi:[0,1]
	v_pk_add_f32 v[116:117], v[84:85], v[140:141] neg_lo:[0,1] neg_hi:[0,1]
	v_pk_add_f32 v[118:119], v[86:87], v[142:143] neg_lo:[0,1] neg_hi:[0,1]
	v_pk_add_f32 v[120:121], v[88:89], v[144:145] neg_lo:[0,1] neg_hi:[0,1]
	v_pk_add_f32 v[122:123], v[90:91], v[146:147] neg_lo:[0,1] neg_hi:[0,1]
	v_pk_add_f32 v[124:125], v[92:93], v[148:149] neg_lo:[0,1] neg_hi:[0,1]
	v_pk_add_f32 v[126:127], v[94:95], v[150:151] neg_lo:[0,1] neg_hi:[0,1]
	global_store_dwordx2 v200, v[170:171], s[10:11]
	global_store_dwordx2 v200, v[172:173], s[10:11] offset:512
	global_store_dwordx2 v200, v[174:175], s[10:11] offset:1024
	global_store_dwordx2 v200, v[176:177], s[10:11] offset:1536
	v_pk_fma_f32 v[96:97], v[112:113], v[16:17], v[136:137]
	v_pk_fma_f32 v[98:99], v[114:115], v[18:19], v[138:139]
	v_pk_fma_f32 v[100:101], v[116:117], v[20:21], v[140:141]
	v_pk_fma_f32 v[102:103], v[118:119], v[22:23], v[142:143]
	v_pk_fma_f32 v[104:105], v[120:121], v[24:25], v[144:145]
	v_pk_fma_f32 v[106:107], v[122:123], v[26:27], v[146:147]
	v_pk_fma_f32 v[108:109], v[124:125], v[28:29], v[148:149]
	v_pk_fma_f32 v[110:111], v[126:127], v[30:31], v[150:151]
	v_cvt_pk_bf16_f32 v178, v96, v97
	v_cvt_pk_bf16_f32 v179, v98, v99
	v_cvt_pk_bf16_f32 v180, v100, v101
	v_cvt_pk_bf16_f32 v181, v102, v103
	v_cvt_pk_bf16_f32 v182, v104, v105
	v_cvt_pk_bf16_f32 v183, v106, v107
	v_cvt_pk_bf16_f32 v184, v108, v109
	v_cvt_pk_bf16_f32 v185, v110, v111
	global_store_dwordx2 v200, v[178:179], s[6:7]
	global_store_dwordx2 v200, v[180:181], s[6:7] offset:512
	global_store_dwordx2 v200, v[182:183], s[6:7] offset:1024
	global_store_dwordx2 v200, v[184:185], s[6:7] offset:1536
	v_pk_fma_f32 v[96:97], v[112:113], v[32:33], v[136:137]
	v_pk_fma_f32 v[98:99], v[114:115], v[34:35], v[138:139]
	v_pk_fma_f32 v[100:101], v[116:117], v[36:37], v[140:141]
	v_pk_fma_f32 v[102:103], v[118:119], v[38:39], v[142:143]
	v_pk_fma_f32 v[104:105], v[120:121], v[40:41], v[144:145]
	v_pk_fma_f32 v[106:107], v[122:123], v[42:43], v[146:147]
	v_pk_fma_f32 v[108:109], v[124:125], v[44:45], v[148:149]
	v_pk_fma_f32 v[110:111], v[126:127], v[46:47], v[150:151]
	v_cvt_pk_bf16_f32 v186, v96, v97
	v_cvt_pk_bf16_f32 v187, v98, v99
	v_cvt_pk_bf16_f32 v188, v100, v101
	v_cvt_pk_bf16_f32 v189, v102, v103
	v_cvt_pk_bf16_f32 v190, v104, v105
	v_cvt_pk_bf16_f32 v191, v106, v107
	v_cvt_pk_bf16_f32 v192, v108, v109
	v_cvt_pk_bf16_f32 v193, v110, v111
	global_store_dwordx2 v200, v[186:187], s[8:9]
	global_store_dwordx2 v200, v[188:189], s[8:9] offset:512
	global_store_dwordx2 v200, v[190:191], s[8:9] offset:1024
	global_store_dwordx2 v200, v[192:193], s[8:9] offset:1536
	v_add_u32_e32 v200, 0x800, v200
	s_waitcnt vmcnt(12)
	global_load_dwordx4 v[48:51], v199, s[12:13]
	global_load_dwordx4 v[52:55], v199, s[12:13] offset:1024
	global_load_dwordx4 v[56:59], v199, s[12:13] offset:2048
	global_load_dwordx4 v[60:63], v199, s[12:13] offset:3072
	v_add_u32_e32 v199, 0x1000, v199
	v_pk_mul_f32 v[128:129], v[64:65], v[64:65]
	v_pk_fma_f32 v[128:129], v[66:67], v[66:67], v[128:129]
	v_pk_fma_f32 v[128:129], v[68:69], v[68:69], v[128:129]
	v_pk_fma_f32 v[128:129], v[70:71], v[70:71], v[128:129]
	v_pk_fma_f32 v[128:129], v[72:73], v[72:73], v[128:129]
	v_pk_fma_f32 v[128:129], v[74:75], v[74:75], v[128:129]
	v_pk_fma_f32 v[128:129], v[76:77], v[76:77], v[128:129]
	v_pk_fma_f32 v[128:129], v[78:79], v[78:79], v[128:129]
	s_nop 0
	v_add_f32_e32 v128, v128, v129
	s_nop 1
	v_add_f32_dpp v128, v128, v128 quad_perm:[1,0,3,2] row_mask:0xf bank_mask:0xf bound_ctrl:1
	s_nop 1
	v_add_f32_dpp v128, v128, v128 quad_perm:[2,3,0,1] row_mask:0xf bank_mask:0xf bound_ctrl:1
	s_nop 1
	v_add_f32_dpp v128, v128, v128 row_half_mirror row_mask:0xf bank_mask:0xf bound_ctrl:1
	s_nop 1
	v_add_f32_dpp v128, v128, v128 row_mirror row_mask:0xf bank_mask:0xf bound_ctrl:1
	s_nop 1
	v_readlane_b32 s20, v128, 0
	v_readlane_b32 s21, v128, 32
	v_readlane_b32 s22, v128, 16
	v_readlane_b32 s23, v128, 48
	s_nop 1
	v_mov_b32_e32 v130, s22
	v_mov_b32_e32 v131, s23
	v_pk_add_f32 v[130:131], s[20:21], v[130:131]
	s_nop 0
	v_add_f32_e32 v130, v130, v131
	v_fma_f32 v130, v130, v194, v195
	v_rsq_f32_e32 v130, v130
	s_nop 0
	v_pk_mul_f32 v[96:97], v[64:65], v[130:131] op_sel_hi:[1,0]
	v_pk_mul_f32 v[98:99], v[66:67], v[130:131] op_sel_hi:[1,0]
	v_pk_mul_f32 v[100:101], v[68:69], v[130:131] op_sel_hi:[1,0]
	v_pk_mul_f32 v[102:103], v[70:71], v[130:131] op_sel_hi:[1,0]
	v_pk_mul_f32 v[104:105], v[72:73], v[130:131] op_sel_hi:[1,0]
	v_pk_mul_f32 v[106:107], v[74:75], v[130:131] op_sel_hi:[1,0]
	v_pk_mul_f32 v[108:109], v[76:77], v[130:131] op_sel_hi:[1,0]
	v_pk_mul_f32 v[110:111], v[78:79], v[130:131] op_sel_hi:[1,0]
	v_pk_mul_f32 v[96:97], v[0:1], v[96:97]
	v_pk_mul_f32 v[98:99], v[2:3], v[98:99]
	v_pk_mul_f32 v[100:101], v[4:5], v[100:101]
	v_pk_mul_f32 v[102:103], v[6:7], v[102:103]
	v_pk_mul_f32 v[104:105], v[8:9], v[104:105]
	v_pk_mul_f32 v[106:107], v[10:11], v[106:107]
	v_pk_mul_f32 v[108:109], v[12:13], v[108:109]
	v_pk_mul_f32 v[110:111], v[14:15], v[110:111]
	v_cvt_pk_bf16_f32 v170, v96, v97
	v_cvt_pk_bf16_f32 v171, v98, v99
	v_cvt_pk_bf16_f32 v172, v100, v101
	v_cvt_pk_bf16_f32 v173, v102, v103
	v_cvt_pk_bf16_f32 v174, v104, v105
	v_cvt_pk_bf16_f32 v175, v106, v107
	v_cvt_pk_bf16_f32 v176, v108, v109
	v_cvt_pk_bf16_f32 v177, v110, v111
	v_lshlrev_b32_e32 v80, 16, v170
	v_and_b32_e32 v81, 0xffff0000, v170
	v_lshlrev_b32_e32 v82, 16, v171
	v_and_b32_e32 v83, 0xffff0000, v171
	v_lshlrev_b32_e32 v84, 16, v172
	v_and_b32_e32 v85, 0xffff0000, v172
	v_lshlrev_b32_e32 v86, 16, v173
	v_and_b32_e32 v87, 0xffff0000, v173
	v_lshlrev_b32_e32 v88, 16, v174
	v_and_b32_e32 v89, 0xffff0000, v174
	v_lshlrev_b32_e32 v90, 16, v175
	v_and_b32_e32 v91, 0xffff0000, v175
	v_lshlrev_b32_e32 v92, 16, v176
	v_and_b32_e32 v93, 0xffff0000, v176
	v_lshlrev_b32_e32 v94, 16, v177
	v_and_b32_e32 v95, 0xffff0000, v177
	v_pk_add_f32 v[112:113], v[136:137], v[80:81] neg_lo:[0,1] neg_hi:[0,1]
	v_pk_add_f32 v[114:115], v[138:139], v[82:83] neg_lo:[0,1] neg_hi:[0,1]
	v_pk_add_f32 v[116:117], v[140:141], v[84:85] neg_lo:[0,1] neg_hi:[0,1]
	v_pk_add_f32 v[118:119], v[142:143], v[86:87] neg_lo:[0,1] neg_hi:[0,1]
	v_pk_add_f32 v[120:121], v[144:145], v[88:89] neg_lo:[0,1] neg_hi:[0,1]
	v_pk_add_f32 v[122:123], v[146:147], v[90:91] neg_lo:[0,1] neg_hi:[0,1]
	v_pk_add_f32 v[124:125], v[148:149], v[92:93] neg_lo:[0,1] neg_hi:[0,1]
	v_pk_add_f32 v[126:127], v[150:151], v[94:95] neg_lo:[0,1] neg_hi:[0,1]
	global_store_dwordx2 v200, v[170:171], s[10:11]
	global_store_dwordx2 v200, v[172:173], s[10:11] offset:512
	global_store_dwordx2 v200, v[174:175], s[10:11] offset:1024
	global_store_dwordx2 v200, v[176:177], s[10:11] offset:1536
	v_pk_fma_f32 v[96:97], v[112:113], v[16:17], v[80:81]
	v_pk_fma_f32 v[98:99], v[114:115], v[18:19], v[82:83]
	v_pk_fma_f32 v[100:101], v[116:117], v[20:21], v[84:85]
	v_pk_fma_f32 v[102:103], v[118:119], v[22:23], v[86:87]
	v_pk_fma_f32 v[104:105], v[120:121], v[24:25], v[88:89]
	v_pk_fma_f32 v[106:107], v[122:123], v[26:27], v[90:91]
	v_pk_fma_f32 v[108:109], v[124:125], v[28:29], v[92:93]
	v_pk_fma_f32 v[110:111], v[126:127], v[30:31], v[94:95]
	v_cvt_pk_bf16_f32 v178, v96, v97
	v_cvt_pk_bf16_f32 v179, v98, v99
	v_cvt_pk_bf16_f32 v180, v100, v101
	v_cvt_pk_bf16_f32 v181, v102, v103
	v_cvt_pk_bf16_f32 v182, v104, v105
	v_cvt_pk_bf16_f32 v183, v106, v107
	v_cvt_pk_bf16_f32 v184, v108, v109
	v_cvt_pk_bf16_f32 v185, v110, v111
	global_store_dwordx2 v200, v[178:179], s[6:7]
	global_store_dwordx2 v200, v[180:181], s[6:7] offset:512
	global_store_dwordx2 v200, v[182:183], s[6:7] offset:1024
	global_store_dwordx2 v200, v[184:185], s[6:7] offset:1536
	v_pk_fma_f32 v[96:97], v[112:113], v[32:33], v[80:81]
	v_pk_fma_f32 v[98:99], v[114:115], v[34:35], v[82:83]
	v_pk_fma_f32 v[100:101], v[116:117], v[36:37], v[84:85]
	v_pk_fma_f32 v[102:103], v[118:119], v[38:39], v[86:87]
	v_pk_fma_f32 v[104:105], v[120:121], v[40:41], v[88:89]
	v_pk_fma_f32 v[106:107], v[122:123], v[42:43], v[90:91]
	v_pk_fma_f32 v[108:109], v[124:125], v[44:45], v[92:93]
	v_pk_fma_f32 v[110:111], v[126:127], v[46:47], v[94:95]
	v_cvt_pk_bf16_f32 v186, v96, v97
	v_cvt_pk_bf16_f32 v187, v98, v99
	v_cvt_pk_bf16_f32 v188, v100, v101
	v_cvt_pk_bf16_f32 v189, v102, v103
	v_cvt_pk_bf16_f32 v190, v104, v105
	v_cvt_pk_bf16_f32 v191, v106, v107
	v_cvt_pk_bf16_f32 v192, v108, v109
	v_cvt_pk_bf16_f32 v193, v110, v111
	global_store_dwordx2 v200, v[186:187], s[8:9]
	global_store_dwordx2 v200, v[188:189], s[8:9] offset:512
	global_store_dwordx2 v200, v[190:191], s[8:9] offset:1024
	global_store_dwordx2 v200, v[192:193], s[8:9] offset:1536
	v_add_u32_e32 v200, 0x800, v200
	s_waitcnt vmcnt(12)
	global_load_dwordx4 v[64:67], v199, s[12:13]
	global_load_dwordx4 v[68:71], v199, s[12:13] offset:1024
	global_load_dwordx4 v[72:75], v199, s[12:13] offset:2048
	global_load_dwordx4 v[76:79], v199, s[12:13] offset:3072
	v_add_u32_e32 v199, 0x1000, v199
	v_pk_mul_f32 v[128:129], v[48:49], v[48:49]
	v_pk_fma_f32 v[128:129], v[50:51], v[50:51], v[128:129]
	v_pk_fma_f32 v[128:129], v[52:53], v[52:53], v[128:129]
	v_pk_fma_f32 v[128:129], v[54:55], v[54:55], v[128:129]
	v_pk_fma_f32 v[128:129], v[56:57], v[56:57], v[128:129]
	v_pk_fma_f32 v[128:129], v[58:59], v[58:59], v[128:129]
	v_pk_fma_f32 v[128:129], v[60:61], v[60:61], v[128:129]
	v_pk_fma_f32 v[128:129], v[62:63], v[62:63], v[128:129]
	s_nop 0
	v_add_f32_e32 v128, v128, v129
	s_nop 1
	v_add_f32_dpp v128, v128, v128 quad_perm:[1,0,3,2] row_mask:0xf bank_mask:0xf bound_ctrl:1
	s_nop 1
	v_add_f32_dpp v128, v128, v128 quad_perm:[2,3,0,1] row_mask:0xf bank_mask:0xf bound_ctrl:1
	s_nop 1
	v_add_f32_dpp v128, v128, v128 row_half_mirror row_mask:0xf bank_mask:0xf bound_ctrl:1
	s_nop 1
	v_add_f32_dpp v128, v128, v128 row_mirror row_mask:0xf bank_mask:0xf bound_ctrl:1
	s_nop 1
	v_readlane_b32 s20, v128, 0
	v_readlane_b32 s21, v128, 32
	v_readlane_b32 s22, v128, 16
	v_readlane_b32 s23, v128, 48
	s_nop 1
	v_mov_b32_e32 v130, s22
	v_mov_b32_e32 v131, s23
	v_pk_add_f32 v[130:131], s[20:21], v[130:131]
	s_nop 0
	v_add_f32_e32 v130, v130, v131
	v_fma_f32 v130, v130, v194, v195
	v_rsq_f32_e32 v130, v130
	s_nop 0
	v_pk_mul_f32 v[96:97], v[48:49], v[130:131] op_sel_hi:[1,0]
	v_pk_mul_f32 v[98:99], v[50:51], v[130:131] op_sel_hi:[1,0]
	v_pk_mul_f32 v[100:101], v[52:53], v[130:131] op_sel_hi:[1,0]
	v_pk_mul_f32 v[102:103], v[54:55], v[130:131] op_sel_hi:[1,0]
	v_pk_mul_f32 v[104:105], v[56:57], v[130:131] op_sel_hi:[1,0]
	v_pk_mul_f32 v[106:107], v[58:59], v[130:131] op_sel_hi:[1,0]
	v_pk_mul_f32 v[108:109], v[60:61], v[130:131] op_sel_hi:[1,0]
	v_pk_mul_f32 v[110:111], v[62:63], v[130:131] op_sel_hi:[1,0]
	v_pk_mul_f32 v[96:97], v[0:1], v[96:97]
	v_pk_mul_f32 v[98:99], v[2:3], v[98:99]
	v_pk_mul_f32 v[100:101], v[4:5], v[100:101]
	v_pk_mul_f32 v[102:103], v[6:7], v[102:103]
	v_pk_mul_f32 v[104:105], v[8:9], v[104:105]
	v_pk_mul_f32 v[106:107], v[10:11], v[106:107]
	v_pk_mul_f32 v[108:109], v[12:13], v[108:109]
	v_pk_mul_f32 v[110:111], v[14:15], v[110:111]
	v_cvt_pk_bf16_f32 v170, v96, v97
	v_cvt_pk_bf16_f32 v171, v98, v99
	v_cvt_pk_bf16_f32 v172, v100, v101
	v_cvt_pk_bf16_f32 v173, v102, v103
	v_cvt_pk_bf16_f32 v174, v104, v105
	v_cvt_pk_bf16_f32 v175, v106, v107
	v_cvt_pk_bf16_f32 v176, v108, v109
	v_cvt_pk_bf16_f32 v177, v110, v111
	v_lshlrev_b32_e32 v136, 16, v170
	v_and_b32_e32 v137, 0xffff0000, v170
	v_lshlrev_b32_e32 v138, 16, v171
	v_and_b32_e32 v139, 0xffff0000, v171
	v_lshlrev_b32_e32 v140, 16, v172
	v_and_b32_e32 v141, 0xffff0000, v172
	v_lshlrev_b32_e32 v142, 16, v173
	v_and_b32_e32 v143, 0xffff0000, v173
	v_lshlrev_b32_e32 v144, 16, v174
	v_and_b32_e32 v145, 0xffff0000, v174
	v_lshlrev_b32_e32 v146, 16, v175
	v_and_b32_e32 v147, 0xffff0000, v175
	v_lshlrev_b32_e32 v148, 16, v176
	v_and_b32_e32 v149, 0xffff0000, v176
	v_lshlrev_b32_e32 v150, 16, v177
	v_and_b32_e32 v151, 0xffff0000, v177
	v_pk_add_f32 v[112:113], v[80:81], v[136:137] neg_lo:[0,1] neg_hi:[0,1]
	v_pk_add_f32 v[114:115], v[82:83], v[138:139] neg_lo:[0,1] neg_hi:[0,1]
	v_pk_add_f32 v[116:117], v[84:85], v[140:141] neg_lo:[0,1] neg_hi:[0,1]
	v_pk_add_f32 v[118:119], v[86:87], v[142:143] neg_lo:[0,1] neg_hi:[0,1]
	v_pk_add_f32 v[120:121], v[88:89], v[144:145] neg_lo:[0,1] neg_hi:[0,1]
	v_pk_add_f32 v[122:123], v[90:91], v[146:147] neg_lo:[0,1] neg_hi:[0,1]
	v_pk_add_f32 v[124:125], v[92:93], v[148:149] neg_lo:[0,1] neg_hi:[0,1]
	v_pk_add_f32 v[126:127], v[94:95], v[150:151] neg_lo:[0,1] neg_hi:[0,1]
	global_store_dwordx2 v200, v[170:171], s[10:11]
	global_store_dwordx2 v200, v[172:173], s[10:11] offset:512
	global_store_dwordx2 v200, v[174:175], s[10:11] offset:1024
	global_store_dwordx2 v200, v[176:177], s[10:11] offset:1536
	v_pk_fma_f32 v[96:97], v[112:113], v[16:17], v[136:137]
	v_pk_fma_f32 v[98:99], v[114:115], v[18:19], v[138:139]
	v_pk_fma_f32 v[100:101], v[116:117], v[20:21], v[140:141]
	v_pk_fma_f32 v[102:103], v[118:119], v[22:23], v[142:143]
	v_pk_fma_f32 v[104:105], v[120:121], v[24:25], v[144:145]
	v_pk_fma_f32 v[106:107], v[122:123], v[26:27], v[146:147]
	v_pk_fma_f32 v[108:109], v[124:125], v[28:29], v[148:149]
	v_pk_fma_f32 v[110:111], v[126:127], v[30:31], v[150:151]
	v_cvt_pk_bf16_f32 v178, v96, v97
	v_cvt_pk_bf16_f32 v179, v98, v99
	v_cvt_pk_bf16_f32 v180, v100, v101
	v_cvt_pk_bf16_f32 v181, v102, v103
	v_cvt_pk_bf16_f32 v182, v104, v105
	v_cvt_pk_bf16_f32 v183, v106, v107
	v_cvt_pk_bf16_f32 v184, v108, v109
	v_cvt_pk_bf16_f32 v185, v110, v111
	global_store_dwordx2 v200, v[178:179], s[6:7]
	global_store_dwordx2 v200, v[180:181], s[6:7] offset:512
	global_store_dwordx2 v200, v[182:183], s[6:7] offset:1024
	global_store_dwordx2 v200, v[184:185], s[6:7] offset:1536
	v_pk_fma_f32 v[96:97], v[112:113], v[32:33], v[136:137]
	v_pk_fma_f32 v[98:99], v[114:115], v[34:35], v[138:139]
	v_pk_fma_f32 v[100:101], v[116:117], v[36:37], v[140:141]
	v_pk_fma_f32 v[102:103], v[118:119], v[38:39], v[142:143]
	v_pk_fma_f32 v[104:105], v[120:121], v[40:41], v[144:145]
	v_pk_fma_f32 v[106:107], v[122:123], v[42:43], v[146:147]
	v_pk_fma_f32 v[108:109], v[124:125], v[44:45], v[148:149]
	v_pk_fma_f32 v[110:111], v[126:127], v[46:47], v[150:151]
	v_cvt_pk_bf16_f32 v186, v96, v97
	v_cvt_pk_bf16_f32 v187, v98, v99
	v_cvt_pk_bf16_f32 v188, v100, v101
	v_cvt_pk_bf16_f32 v189, v102, v103
	v_cvt_pk_bf16_f32 v190, v104, v105
	v_cvt_pk_bf16_f32 v191, v106, v107
	v_cvt_pk_bf16_f32 v192, v108, v109
	v_cvt_pk_bf16_f32 v193, v110, v111
	global_store_dwordx2 v200, v[186:187], s[8:9]
	global_store_dwordx2 v200, v[188:189], s[8:9] offset:512
	global_store_dwordx2 v200, v[190:191], s[8:9] offset:1024
	global_store_dwordx2 v200, v[192:193], s[8:9] offset:1536
	v_add_u32_e32 v200, 0x800, v200
	s_waitcnt vmcnt(12)
	global_load_dwordx4 v[48:51], v199, s[12:13]
	global_load_dwordx4 v[52:55], v199, s[12:13] offset:1024
	global_load_dwordx4 v[56:59], v199, s[12:13] offset:2048
	global_load_dwordx4 v[60:63], v199, s[12:13] offset:3072
	v_add_u32_e32 v199, 0x1000, v199
	v_pk_mul_f32 v[128:129], v[64:65], v[64:65]
	v_pk_fma_f32 v[128:129], v[66:67], v[66:67], v[128:129]
	v_pk_fma_f32 v[128:129], v[68:69], v[68:69], v[128:129]
	v_pk_fma_f32 v[128:129], v[70:71], v[70:71], v[128:129]
	v_pk_fma_f32 v[128:129], v[72:73], v[72:73], v[128:129]
	v_pk_fma_f32 v[128:129], v[74:75], v[74:75], v[128:129]
	v_pk_fma_f32 v[128:129], v[76:77], v[76:77], v[128:129]
	v_pk_fma_f32 v[128:129], v[78:79], v[78:79], v[128:129]
	s_nop 0
	v_add_f32_e32 v128, v128, v129
	s_nop 1
	v_add_f32_dpp v128, v128, v128 quad_perm:[1,0,3,2] row_mask:0xf bank_mask:0xf bound_ctrl:1
	s_nop 1
	v_add_f32_dpp v128, v128, v128 quad_perm:[2,3,0,1] row_mask:0xf bank_mask:0xf bound_ctrl:1
	s_nop 1
	v_add_f32_dpp v128, v128, v128 row_half_mirror row_mask:0xf bank_mask:0xf bound_ctrl:1
	s_nop 1
	v_add_f32_dpp v128, v128, v128 row_mirror row_mask:0xf bank_mask:0xf bound_ctrl:1
	s_nop 1
	v_readlane_b32 s20, v128, 0
	v_readlane_b32 s21, v128, 32
	v_readlane_b32 s22, v128, 16
	v_readlane_b32 s23, v128, 48
	s_nop 1
	v_mov_b32_e32 v130, s22
	v_mov_b32_e32 v131, s23
	v_pk_add_f32 v[130:131], s[20:21], v[130:131]
	s_nop 0
	v_add_f32_e32 v130, v130, v131
	v_fma_f32 v130, v130, v194, v195
	v_rsq_f32_e32 v130, v130
	s_nop 0
	v_pk_mul_f32 v[96:97], v[64:65], v[130:131] op_sel_hi:[1,0]
	v_pk_mul_f32 v[98:99], v[66:67], v[130:131] op_sel_hi:[1,0]
	v_pk_mul_f32 v[100:101], v[68:69], v[130:131] op_sel_hi:[1,0]
	v_pk_mul_f32 v[102:103], v[70:71], v[130:131] op_sel_hi:[1,0]
	v_pk_mul_f32 v[104:105], v[72:73], v[130:131] op_sel_hi:[1,0]
	v_pk_mul_f32 v[106:107], v[74:75], v[130:131] op_sel_hi:[1,0]
	v_pk_mul_f32 v[108:109], v[76:77], v[130:131] op_sel_hi:[1,0]
	v_pk_mul_f32 v[110:111], v[78:79], v[130:131] op_sel_hi:[1,0]
	v_pk_mul_f32 v[96:97], v[0:1], v[96:97]
	v_pk_mul_f32 v[98:99], v[2:3], v[98:99]
	v_pk_mul_f32 v[100:101], v[4:5], v[100:101]
	v_pk_mul_f32 v[102:103], v[6:7], v[102:103]
	v_pk_mul_f32 v[104:105], v[8:9], v[104:105]
	v_pk_mul_f32 v[106:107], v[10:11], v[106:107]
	v_pk_mul_f32 v[108:109], v[12:13], v[108:109]
	v_pk_mul_f32 v[110:111], v[14:15], v[110:111]
	v_cvt_pk_bf16_f32 v170, v96, v97
	v_cvt_pk_bf16_f32 v171, v98, v99
	v_cvt_pk_bf16_f32 v172, v100, v101
	v_cvt_pk_bf16_f32 v173, v102, v103
	v_cvt_pk_bf16_f32 v174, v104, v105
	v_cvt_pk_bf16_f32 v175, v106, v107
	v_cvt_pk_bf16_f32 v176, v108, v109
	v_cvt_pk_bf16_f32 v177, v110, v111
	v_lshlrev_b32_e32 v80, 16, v170
	v_and_b32_e32 v81, 0xffff0000, v170
	v_lshlrev_b32_e32 v82, 16, v171
	v_and_b32_e32 v83, 0xffff0000, v171
	v_lshlrev_b32_e32 v84, 16, v172
	v_and_b32_e32 v85, 0xffff0000, v172
	v_lshlrev_b32_e32 v86, 16, v173
	v_and_b32_e32 v87, 0xffff0000, v173
	v_lshlrev_b32_e32 v88, 16, v174
	v_and_b32_e32 v89, 0xffff0000, v174
	v_lshlrev_b32_e32 v90, 16, v175
	v_and_b32_e32 v91, 0xffff0000, v175
	v_lshlrev_b32_e32 v92, 16, v176
	v_and_b32_e32 v93, 0xffff0000, v176
	v_lshlrev_b32_e32 v94, 16, v177
	v_and_b32_e32 v95, 0xffff0000, v177
	v_pk_add_f32 v[112:113], v[136:137], v[80:81] neg_lo:[0,1] neg_hi:[0,1]
	v_pk_add_f32 v[114:115], v[138:139], v[82:83] neg_lo:[0,1] neg_hi:[0,1]
	v_pk_add_f32 v[116:117], v[140:141], v[84:85] neg_lo:[0,1] neg_hi:[0,1]
	v_pk_add_f32 v[118:119], v[142:143], v[86:87] neg_lo:[0,1] neg_hi:[0,1]
	v_pk_add_f32 v[120:121], v[144:145], v[88:89] neg_lo:[0,1] neg_hi:[0,1]
	v_pk_add_f32 v[122:123], v[146:147], v[90:91] neg_lo:[0,1] neg_hi:[0,1]
	v_pk_add_f32 v[124:125], v[148:149], v[92:93] neg_lo:[0,1] neg_hi:[0,1]
	v_pk_add_f32 v[126:127], v[150:151], v[94:95] neg_lo:[0,1] neg_hi:[0,1]
	global_store_dwordx2 v200, v[170:171], s[10:11]
	global_store_dwordx2 v200, v[172:173], s[10:11] offset:512
	global_store_dwordx2 v200, v[174:175], s[10:11] offset:1024
	global_store_dwordx2 v200, v[176:177], s[10:11] offset:1536
	v_pk_fma_f32 v[96:97], v[112:113], v[16:17], v[80:81]
	v_pk_fma_f32 v[98:99], v[114:115], v[18:19], v[82:83]
	v_pk_fma_f32 v[100:101], v[116:117], v[20:21], v[84:85]
	v_pk_fma_f32 v[102:103], v[118:119], v[22:23], v[86:87]
	v_pk_fma_f32 v[104:105], v[120:121], v[24:25], v[88:89]
	v_pk_fma_f32 v[106:107], v[122:123], v[26:27], v[90:91]
	v_pk_fma_f32 v[108:109], v[124:125], v[28:29], v[92:93]
	v_pk_fma_f32 v[110:111], v[126:127], v[30:31], v[94:95]
	v_cvt_pk_bf16_f32 v178, v96, v97
	v_cvt_pk_bf16_f32 v179, v98, v99
	v_cvt_pk_bf16_f32 v180, v100, v101
	v_cvt_pk_bf16_f32 v181, v102, v103
	v_cvt_pk_bf16_f32 v182, v104, v105
	v_cvt_pk_bf16_f32 v183, v106, v107
	v_cvt_pk_bf16_f32 v184, v108, v109
	v_cvt_pk_bf16_f32 v185, v110, v111
	global_store_dwordx2 v200, v[178:179], s[6:7]
	global_store_dwordx2 v200, v[180:181], s[6:7] offset:512
	global_store_dwordx2 v200, v[182:183], s[6:7] offset:1024
	global_store_dwordx2 v200, v[184:185], s[6:7] offset:1536
	v_pk_fma_f32 v[96:97], v[112:113], v[32:33], v[80:81]
	v_pk_fma_f32 v[98:99], v[114:115], v[34:35], v[82:83]
	v_pk_fma_f32 v[100:101], v[116:117], v[36:37], v[84:85]
	v_pk_fma_f32 v[102:103], v[118:119], v[38:39], v[86:87]
	v_pk_fma_f32 v[104:105], v[120:121], v[40:41], v[88:89]
	v_pk_fma_f32 v[106:107], v[122:123], v[42:43], v[90:91]
	v_pk_fma_f32 v[108:109], v[124:125], v[44:45], v[92:93]
	v_pk_fma_f32 v[110:111], v[126:127], v[46:47], v[94:95]
	v_cvt_pk_bf16_f32 v186, v96, v97
	v_cvt_pk_bf16_f32 v187, v98, v99
	v_cvt_pk_bf16_f32 v188, v100, v101
	v_cvt_pk_bf16_f32 v189, v102, v103
	v_cvt_pk_bf16_f32 v190, v104, v105
	v_cvt_pk_bf16_f32 v191, v106, v107
	v_cvt_pk_bf16_f32 v192, v108, v109
	v_cvt_pk_bf16_f32 v193, v110, v111
	global_store_dwordx2 v200, v[186:187], s[8:9]
	global_store_dwordx2 v200, v[188:189], s[8:9] offset:512
	global_store_dwordx2 v200, v[190:191], s[8:9] offset:1024
	global_store_dwordx2 v200, v[192:193], s[8:9] offset:1536
	v_add_u32_e32 v200, 0x800, v200
	s_waitcnt vmcnt(12)
	global_load_dwordx4 v[64:67], v199, s[12:13]
	global_load_dwordx4 v[68:71], v199, s[12:13] offset:1024
	global_load_dwordx4 v[72:75], v199, s[12:13] offset:2048
	global_load_dwordx4 v[76:79], v199, s[12:13] offset:3072
	v_add_u32_e32 v199, 0x1000, v199
	v_pk_mul_f32 v[128:129], v[48:49], v[48:49]
	v_pk_fma_f32 v[128:129], v[50:51], v[50:51], v[128:129]
	v_pk_fma_f32 v[128:129], v[52:53], v[52:53], v[128:129]
	v_pk_fma_f32 v[128:129], v[54:55], v[54:55], v[128:129]
	v_pk_fma_f32 v[128:129], v[56:57], v[56:57], v[128:129]
	v_pk_fma_f32 v[128:129], v[58:59], v[58:59], v[128:129]
	v_pk_fma_f32 v[128:129], v[60:61], v[60:61], v[128:129]
	v_pk_fma_f32 v[128:129], v[62:63], v[62:63], v[128:129]
	s_nop 0
	v_add_f32_e32 v128, v128, v129
	s_nop 1
	v_add_f32_dpp v128, v128, v128 quad_perm:[1,0,3,2] row_mask:0xf bank_mask:0xf bound_ctrl:1
	s_nop 1
	v_add_f32_dpp v128, v128, v128 quad_perm:[2,3,0,1] row_mask:0xf bank_mask:0xf bound_ctrl:1
	s_nop 1
	v_add_f32_dpp v128, v128, v128 row_half_mirror row_mask:0xf bank_mask:0xf bound_ctrl:1
	s_nop 1
	v_add_f32_dpp v128, v128, v128 row_mirror row_mask:0xf bank_mask:0xf bound_ctrl:1
	s_nop 1
	v_readlane_b32 s20, v128, 0
	v_readlane_b32 s21, v128, 32
	v_readlane_b32 s22, v128, 16
	v_readlane_b32 s23, v128, 48
	s_nop 1
	v_mov_b32_e32 v130, s22
	v_mov_b32_e32 v131, s23
	v_pk_add_f32 v[130:131], s[20:21], v[130:131]
	s_nop 0
	v_add_f32_e32 v130, v130, v131
	v_fma_f32 v130, v130, v194, v195
	v_rsq_f32_e32 v130, v130
	s_nop 0
	v_pk_mul_f32 v[96:97], v[48:49], v[130:131] op_sel_hi:[1,0]
	v_pk_mul_f32 v[98:99], v[50:51], v[130:131] op_sel_hi:[1,0]
	v_pk_mul_f32 v[100:101], v[52:53], v[130:131] op_sel_hi:[1,0]
	v_pk_mul_f32 v[102:103], v[54:55], v[130:131] op_sel_hi:[1,0]
	v_pk_mul_f32 v[104:105], v[56:57], v[130:131] op_sel_hi:[1,0]
	v_pk_mul_f32 v[106:107], v[58:59], v[130:131] op_sel_hi:[1,0]
	v_pk_mul_f32 v[108:109], v[60:61], v[130:131] op_sel_hi:[1,0]
	v_pk_mul_f32 v[110:111], v[62:63], v[130:131] op_sel_hi:[1,0]
	v_pk_mul_f32 v[96:97], v[0:1], v[96:97]
	v_pk_mul_f32 v[98:99], v[2:3], v[98:99]
	v_pk_mul_f32 v[100:101], v[4:5], v[100:101]
	v_pk_mul_f32 v[102:103], v[6:7], v[102:103]
	v_pk_mul_f32 v[104:105], v[8:9], v[104:105]
	v_pk_mul_f32 v[106:107], v[10:11], v[106:107]
	v_pk_mul_f32 v[108:109], v[12:13], v[108:109]
	v_pk_mul_f32 v[110:111], v[14:15], v[110:111]
	v_cvt_pk_bf16_f32 v170, v96, v97
	v_cvt_pk_bf16_f32 v171, v98, v99
	v_cvt_pk_bf16_f32 v172, v100, v101
	v_cvt_pk_bf16_f32 v173, v102, v103
	v_cvt_pk_bf16_f32 v174, v104, v105
	v_cvt_pk_bf16_f32 v175, v106, v107
	v_cvt_pk_bf16_f32 v176, v108, v109
	v_cvt_pk_bf16_f32 v177, v110, v111
	v_lshlrev_b32_e32 v136, 16, v170
	v_and_b32_e32 v137, 0xffff0000, v170
	v_lshlrev_b32_e32 v138, 16, v171
	v_and_b32_e32 v139, 0xffff0000, v171
	v_lshlrev_b32_e32 v140, 16, v172
	v_and_b32_e32 v141, 0xffff0000, v172
	v_lshlrev_b32_e32 v142, 16, v173
	v_and_b32_e32 v143, 0xffff0000, v173
	v_lshlrev_b32_e32 v144, 16, v174
	v_and_b32_e32 v145, 0xffff0000, v174
	v_lshlrev_b32_e32 v146, 16, v175
	v_and_b32_e32 v147, 0xffff0000, v175
	v_lshlrev_b32_e32 v148, 16, v176
	v_and_b32_e32 v149, 0xffff0000, v176
	v_lshlrev_b32_e32 v150, 16, v177
	v_and_b32_e32 v151, 0xffff0000, v177
	v_pk_add_f32 v[112:113], v[80:81], v[136:137] neg_lo:[0,1] neg_hi:[0,1]
	v_pk_add_f32 v[114:115], v[82:83], v[138:139] neg_lo:[0,1] neg_hi:[0,1]
	v_pk_add_f32 v[116:117], v[84:85], v[140:141] neg_lo:[0,1] neg_hi:[0,1]
	v_pk_add_f32 v[118:119], v[86:87], v[142:143] neg_lo:[0,1] neg_hi:[0,1]
	v_pk_add_f32 v[120:121], v[88:89], v[144:145] neg_lo:[0,1] neg_hi:[0,1]
	v_pk_add_f32 v[122:123], v[90:91], v[146:147] neg_lo:[0,1] neg_hi:[0,1]
	v_pk_add_f32 v[124:125], v[92:93], v[148:149] neg_lo:[0,1] neg_hi:[0,1]
	v_pk_add_f32 v[126:127], v[94:95], v[150:151] neg_lo:[0,1] neg_hi:[0,1]
	global_store_dwordx2 v200, v[170:171], s[10:11]
	global_store_dwordx2 v200, v[172:173], s[10:11] offset:512
	global_store_dwordx2 v200, v[174:175], s[10:11] offset:1024
	global_store_dwordx2 v200, v[176:177], s[10:11] offset:1536
	v_pk_fma_f32 v[96:97], v[112:113], v[16:17], v[136:137]
	v_pk_fma_f32 v[98:99], v[114:115], v[18:19], v[138:139]
	v_pk_fma_f32 v[100:101], v[116:117], v[20:21], v[140:141]
	v_pk_fma_f32 v[102:103], v[118:119], v[22:23], v[142:143]
	v_pk_fma_f32 v[104:105], v[120:121], v[24:25], v[144:145]
	v_pk_fma_f32 v[106:107], v[122:123], v[26:27], v[146:147]
	v_pk_fma_f32 v[108:109], v[124:125], v[28:29], v[148:149]
	v_pk_fma_f32 v[110:111], v[126:127], v[30:31], v[150:151]
	v_cvt_pk_bf16_f32 v178, v96, v97
	v_cvt_pk_bf16_f32 v179, v98, v99
	v_cvt_pk_bf16_f32 v180, v100, v101
	v_cvt_pk_bf16_f32 v181, v102, v103
	v_cvt_pk_bf16_f32 v182, v104, v105
	v_cvt_pk_bf16_f32 v183, v106, v107
	v_cvt_pk_bf16_f32 v184, v108, v109
	v_cvt_pk_bf16_f32 v185, v110, v111
	global_store_dwordx2 v200, v[178:179], s[6:7]
	global_store_dwordx2 v200, v[180:181], s[6:7] offset:512
	global_store_dwordx2 v200, v[182:183], s[6:7] offset:1024
	global_store_dwordx2 v200, v[184:185], s[6:7] offset:1536
	v_pk_fma_f32 v[96:97], v[112:113], v[32:33], v[136:137]
	v_pk_fma_f32 v[98:99], v[114:115], v[34:35], v[138:139]
	v_pk_fma_f32 v[100:101], v[116:117], v[36:37], v[140:141]
	v_pk_fma_f32 v[102:103], v[118:119], v[38:39], v[142:143]
	v_pk_fma_f32 v[104:105], v[120:121], v[40:41], v[144:145]
	v_pk_fma_f32 v[106:107], v[122:123], v[42:43], v[146:147]
	v_pk_fma_f32 v[108:109], v[124:125], v[44:45], v[148:149]
	v_pk_fma_f32 v[110:111], v[126:127], v[46:47], v[150:151]
	v_cvt_pk_bf16_f32 v186, v96, v97
	v_cvt_pk_bf16_f32 v187, v98, v99
	v_cvt_pk_bf16_f32 v188, v100, v101
	v_cvt_pk_bf16_f32 v189, v102, v103
	v_cvt_pk_bf16_f32 v190, v104, v105
	v_cvt_pk_bf16_f32 v191, v106, v107
	v_cvt_pk_bf16_f32 v192, v108, v109
	v_cvt_pk_bf16_f32 v193, v110, v111
	global_store_dwordx2 v200, v[186:187], s[8:9]
	global_store_dwordx2 v200, v[188:189], s[8:9] offset:512
	global_store_dwordx2 v200, v[190:191], s[8:9] offset:1024
	global_store_dwordx2 v200, v[192:193], s[8:9] offset:1536
	v_add_u32_e32 v200, 0x800, v200
	s_waitcnt vmcnt(12)
	global_load_dwordx4 v[48:51], v199, s[12:13]
	global_load_dwordx4 v[52:55], v199, s[12:13] offset:1024
	global_load_dwordx4 v[56:59], v199, s[12:13] offset:2048
	global_load_dwordx4 v[60:63], v199, s[12:13] offset:3072
	v_add_u32_e32 v199, 0x1000, v199
	v_pk_mul_f32 v[128:129], v[64:65], v[64:65]
	v_pk_fma_f32 v[128:129], v[66:67], v[66:67], v[128:129]
	v_pk_fma_f32 v[128:129], v[68:69], v[68:69], v[128:129]
	v_pk_fma_f32 v[128:129], v[70:71], v[70:71], v[128:129]
	v_pk_fma_f32 v[128:129], v[72:73], v[72:73], v[128:129]
	v_pk_fma_f32 v[128:129], v[74:75], v[74:75], v[128:129]
	v_pk_fma_f32 v[128:129], v[76:77], v[76:77], v[128:129]
	v_pk_fma_f32 v[128:129], v[78:79], v[78:79], v[128:129]
	s_nop 0
	v_add_f32_e32 v128, v128, v129
	s_nop 1
	v_add_f32_dpp v128, v128, v128 quad_perm:[1,0,3,2] row_mask:0xf bank_mask:0xf bound_ctrl:1
	s_nop 1
	v_add_f32_dpp v128, v128, v128 quad_perm:[2,3,0,1] row_mask:0xf bank_mask:0xf bound_ctrl:1
	s_nop 1
	v_add_f32_dpp v128, v128, v128 row_half_mirror row_mask:0xf bank_mask:0xf bound_ctrl:1
	s_nop 1
	v_add_f32_dpp v128, v128, v128 row_mirror row_mask:0xf bank_mask:0xf bound_ctrl:1
	s_nop 1
	v_readlane_b32 s20, v128, 0
	v_readlane_b32 s21, v128, 32
	v_readlane_b32 s22, v128, 16
	v_readlane_b32 s23, v128, 48
	s_nop 1
	v_mov_b32_e32 v130, s22
	v_mov_b32_e32 v131, s23
	v_pk_add_f32 v[130:131], s[20:21], v[130:131]
	s_nop 0
	v_add_f32_e32 v130, v130, v131
	v_fma_f32 v130, v130, v194, v195
	v_rsq_f32_e32 v130, v130
	s_nop 0
	v_pk_mul_f32 v[96:97], v[64:65], v[130:131] op_sel_hi:[1,0]
	v_pk_mul_f32 v[98:99], v[66:67], v[130:131] op_sel_hi:[1,0]
	v_pk_mul_f32 v[100:101], v[68:69], v[130:131] op_sel_hi:[1,0]
	v_pk_mul_f32 v[102:103], v[70:71], v[130:131] op_sel_hi:[1,0]
	v_pk_mul_f32 v[104:105], v[72:73], v[130:131] op_sel_hi:[1,0]
	v_pk_mul_f32 v[106:107], v[74:75], v[130:131] op_sel_hi:[1,0]
	v_pk_mul_f32 v[108:109], v[76:77], v[130:131] op_sel_hi:[1,0]
	v_pk_mul_f32 v[110:111], v[78:79], v[130:131] op_sel_hi:[1,0]
	v_pk_mul_f32 v[96:97], v[0:1], v[96:97]
	v_pk_mul_f32 v[98:99], v[2:3], v[98:99]
	v_pk_mul_f32 v[100:101], v[4:5], v[100:101]
	v_pk_mul_f32 v[102:103], v[6:7], v[102:103]
	v_pk_mul_f32 v[104:105], v[8:9], v[104:105]
	v_pk_mul_f32 v[106:107], v[10:11], v[106:107]
	v_pk_mul_f32 v[108:109], v[12:13], v[108:109]
	v_pk_mul_f32 v[110:111], v[14:15], v[110:111]
	v_cvt_pk_bf16_f32 v170, v96, v97
	v_cvt_pk_bf16_f32 v171, v98, v99
	v_cvt_pk_bf16_f32 v172, v100, v101
	v_cvt_pk_bf16_f32 v173, v102, v103
	v_cvt_pk_bf16_f32 v174, v104, v105
	v_cvt_pk_bf16_f32 v175, v106, v107
	v_cvt_pk_bf16_f32 v176, v108, v109
	v_cvt_pk_bf16_f32 v177, v110, v111
	v_lshlrev_b32_e32 v80, 16, v170
	v_and_b32_e32 v81, 0xffff0000, v170
	v_lshlrev_b32_e32 v82, 16, v171
	v_and_b32_e32 v83, 0xffff0000, v171
	v_lshlrev_b32_e32 v84, 16, v172
	v_and_b32_e32 v85, 0xffff0000, v172
	v_lshlrev_b32_e32 v86, 16, v173
	v_and_b32_e32 v87, 0xffff0000, v173
	v_lshlrev_b32_e32 v88, 16, v174
	v_and_b32_e32 v89, 0xffff0000, v174
	v_lshlrev_b32_e32 v90, 16, v175
	v_and_b32_e32 v91, 0xffff0000, v175
	v_lshlrev_b32_e32 v92, 16, v176
	v_and_b32_e32 v93, 0xffff0000, v176
	v_lshlrev_b32_e32 v94, 16, v177
	v_and_b32_e32 v95, 0xffff0000, v177
	v_pk_add_f32 v[112:113], v[136:137], v[80:81] neg_lo:[0,1] neg_hi:[0,1]
	v_pk_add_f32 v[114:115], v[138:139], v[82:83] neg_lo:[0,1] neg_hi:[0,1]
	v_pk_add_f32 v[116:117], v[140:141], v[84:85] neg_lo:[0,1] neg_hi:[0,1]
	v_pk_add_f32 v[118:119], v[142:143], v[86:87] neg_lo:[0,1] neg_hi:[0,1]
	v_pk_add_f32 v[120:121], v[144:145], v[88:89] neg_lo:[0,1] neg_hi:[0,1]
	v_pk_add_f32 v[122:123], v[146:147], v[90:91] neg_lo:[0,1] neg_hi:[0,1]
	v_pk_add_f32 v[124:125], v[148:149], v[92:93] neg_lo:[0,1] neg_hi:[0,1]
	v_pk_add_f32 v[126:127], v[150:151], v[94:95] neg_lo:[0,1] neg_hi:[0,1]
	global_store_dwordx2 v200, v[170:171], s[10:11]
	global_store_dwordx2 v200, v[172:173], s[10:11] offset:512
	global_store_dwordx2 v200, v[174:175], s[10:11] offset:1024
	global_store_dwordx2 v200, v[176:177], s[10:11] offset:1536
	v_pk_fma_f32 v[96:97], v[112:113], v[16:17], v[80:81]
	v_pk_fma_f32 v[98:99], v[114:115], v[18:19], v[82:83]
	v_pk_fma_f32 v[100:101], v[116:117], v[20:21], v[84:85]
	v_pk_fma_f32 v[102:103], v[118:119], v[22:23], v[86:87]
	v_pk_fma_f32 v[104:105], v[120:121], v[24:25], v[88:89]
	v_pk_fma_f32 v[106:107], v[122:123], v[26:27], v[90:91]
	v_pk_fma_f32 v[108:109], v[124:125], v[28:29], v[92:93]
	v_pk_fma_f32 v[110:111], v[126:127], v[30:31], v[94:95]
	v_cvt_pk_bf16_f32 v178, v96, v97
	v_cvt_pk_bf16_f32 v179, v98, v99
	v_cvt_pk_bf16_f32 v180, v100, v101
	v_cvt_pk_bf16_f32 v181, v102, v103
	v_cvt_pk_bf16_f32 v182, v104, v105
	v_cvt_pk_bf16_f32 v183, v106, v107
	v_cvt_pk_bf16_f32 v184, v108, v109
	v_cvt_pk_bf16_f32 v185, v110, v111
	global_store_dwordx2 v200, v[178:179], s[6:7]
	global_store_dwordx2 v200, v[180:181], s[6:7] offset:512
	global_store_dwordx2 v200, v[182:183], s[6:7] offset:1024
	global_store_dwordx2 v200, v[184:185], s[6:7] offset:1536
	v_pk_fma_f32 v[96:97], v[112:113], v[32:33], v[80:81]
	v_pk_fma_f32 v[98:99], v[114:115], v[34:35], v[82:83]
	v_pk_fma_f32 v[100:101], v[116:117], v[36:37], v[84:85]
	v_pk_fma_f32 v[102:103], v[118:119], v[38:39], v[86:87]
	v_pk_fma_f32 v[104:105], v[120:121], v[40:41], v[88:89]
	v_pk_fma_f32 v[106:107], v[122:123], v[42:43], v[90:91]
	v_pk_fma_f32 v[108:109], v[124:125], v[44:45], v[92:93]
	v_pk_fma_f32 v[110:111], v[126:127], v[46:47], v[94:95]
	v_cvt_pk_bf16_f32 v186, v96, v97
	v_cvt_pk_bf16_f32 v187, v98, v99
	v_cvt_pk_bf16_f32 v188, v100, v101
	v_cvt_pk_bf16_f32 v189, v102, v103
	v_cvt_pk_bf16_f32 v190, v104, v105
	v_cvt_pk_bf16_f32 v191, v106, v107
	v_cvt_pk_bf16_f32 v192, v108, v109
	v_cvt_pk_bf16_f32 v193, v110, v111
	global_store_dwordx2 v200, v[186:187], s[8:9]
	global_store_dwordx2 v200, v[188:189], s[8:9] offset:512
	global_store_dwordx2 v200, v[190:191], s[8:9] offset:1024
	global_store_dwordx2 v200, v[192:193], s[8:9] offset:1536
	v_add_u32_e32 v200, 0x800, v200
	s_waitcnt vmcnt(12)
; __device__ __forceinline__ u16 f2bf(float f) { return (u16)(pack2(f, f) & 0xFFFFu); }
; __device__ __forceinline__ float bf2f(u16 h) { return __uint_as_float(((unsigned)h) << 16); }
; __device__ __forceinline__ void norm_mix_phase(const float* x, const float* __restrict__ g, const float* __restrict__ mur, const float* __restrict__ muk,
;                                                u16* H, u16* XR, u16* XK) {
;     ...
;       const float4* xp = (const float4*)(x + (size_t)row * DM);
;       float4 v[4];
;       float ss = 0.f;
; #pragma unroll
;       for (int i = 0; i < 4; ++i) { v[i] = xp[i * 64 + lane]; ss += v[i].x * v[i].x + v[i].y * v[i].y + v[i].z * v[i].z + v[i].w * v[i].w; }
;       ss = wave_allreduce(ss);
;       const float rstd = rsqrtf(ss * (1.0f / DM) + 1e-6f);
;       float h[16];
; #pragma unroll
;       for (int i = 0; i < 4; ++i) {
;         const float4 gg = ((const float4*)g)[i * 64 + lane];
;         h[i * 4 + 0] = v[i].x * rstd * gg.x; h[i * 4 + 1] = v[i].y * rstd * gg.y; h[i * 4 + 2] = v[i].z * rstd * gg.z; h[i * 4 + 3] = v[i].w * rstd * gg.w;
;       }
;       if (row >= r0) {
; #pragma unroll
;         for (int i = 0; i < 4; ++i) {
;           const float4 mr = ((const float4*)mur)[i * 64 + lane], mk = ((const float4*)muk)[i * 64 + lane];
;           const float h0 = bf2f(f2bf(h[i * 4 + 0])), h1 = bf2f(f2bf(h[i * 4 + 1])), h2 = bf2f(f2bf(h[i * 4 + 2])), h3 = bf2f(f2bf(h[i * 4 + 3]));
;           const float p0 = bf2f(f2bf(hp[i * 4 + 0])), p1 = bf2f(f2bf(hp[i * 4 + 1])), p2 = bf2f(f2bf(hp[i * 4 + 2])), p3 = bf2f(f2bf(hp[i * 4 + 3]));
;           uint2 o; o.x = pack2(h[i * 4 + 0], h[i * 4 + 1]); o.y = pack2(h[i * 4 + 2], h[i * 4 + 3]);
;           ((uint2*)(H + (size_t)row * DM))[i * 64 + lane] = o;
;           o.x = pack2(h0 + (p0 - h0) * mr.x, h1 + (p1 - h1) * mr.y); o.y = pack2(h2 + (p2 - h2) * mr.z, h3 + (p3 - h3) * mr.w);
;           ((uint2*)(XR + (size_t)row * DM))[i * 64 + lane] = o;
;           o.x = pack2(h0 + (p0 - h0) * mk.x, h1 + (p1 - h1) * mk.y); o.y = pack2(h2 + (p2 - h2) * mk.z, h3 + (p3 - h3) * mk.w);
;           ((uint2*)(XK + (size_t)row * DM))[i * 64 + lane] = o;
	global_load_dwordx4 v[64:67], v199, s[12:13]
	global_load_dwordx4 v[68:71], v199, s[12:13] offset:1024
	global_load_dwordx4 v[72:75], v199, s[12:13] offset:2048
	global_load_dwordx4 v[76:79], v199, s[12:13] offset:3072
	v_add_u32_e32 v199, 0x1000, v199
	v_pk_mul_f32 v[128:129], v[48:49], v[48:49]
	v_pk_fma_f32 v[128:129], v[50:51], v[50:51], v[128:129]
	v_pk_fma_f32 v[128:129], v[52:53], v[52:53], v[128:129]
	v_pk_fma_f32 v[128:129], v[54:55], v[54:55], v[128:129]
	v_pk_fma_f32 v[128:129], v[56:57], v[56:57], v[128:129]
	v_pk_fma_f32 v[128:129], v[58:59], v[58:59], v[128:129]
	v_pk_fma_f32 v[128:129], v[60:61], v[60:61], v[128:129]
	v_pk_fma_f32 v[128:129], v[62:63], v[62:63], v[128:129]
	s_nop 0
	v_add_f32_e32 v128, v128, v129
	s_nop 1
	v_add_f32_dpp v128, v128, v128 quad_perm:[1,0,3,2] row_mask:0xf bank_mask:0xf bound_ctrl:1
	s_nop 1
	v_add_f32_dpp v128, v128, v128 quad_perm:[2,3,0,1] row_mask:0xf bank_mask:0xf bound_ctrl:1
	s_nop 1
	v_add_f32_dpp v128, v128, v128 row_half_mirror row_mask:0xf bank_mask:0xf bound_ctrl:1
	s_nop 1
	v_add_f32_dpp v128, v128, v128 row_mirror row_mask:0xf bank_mask:0xf bound_ctrl:1
	s_nop 1
	v_readlane_b32 s20, v128, 0
	v_readlane_b32 s21, v128, 32
	v_readlane_b32 s22, v128, 16
	v_readlane_b32 s23, v128, 48
	s_nop 1
	v_mov_b32_e32 v130, s22
	v_mov_b32_e32 v131, s23
	v_pk_add_f32 v[130:131], s[20:21], v[130:131]
	s_nop 0
	v_add_f32_e32 v130, v130, v131
	v_fma_f32 v130, v130, v194, v195
	v_rsq_f32_e32 v130, v130
	s_nop 0
	v_pk_mul_f32 v[96:97], v[48:49], v[130:131] op_sel_hi:[1,0]
	v_pk_mul_f32 v[98:99], v[50:51], v[130:131] op_sel_hi:[1,0]
	v_pk_mul_f32 v[100:101], v[52:53], v[130:131] op_sel_hi:[1,0]
	v_pk_mul_f32 v[102:103], v[54:55], v[130:131] op_sel_hi:[1,0]
	v_pk_mul_f32 v[104:105], v[56:57], v[130:131] op_sel_hi:[1,0]
	v_pk_mul_f32 v[106:107], v[58:59], v[130:131] op_sel_hi:[1,0]
	v_pk_mul_f32 v[108:109], v[60:61], v[130:131] op_sel_hi:[1,0]
	v_pk_mul_f32 v[110:111], v[62:63], v[130:131] op_sel_hi:[1,0]
	v_pk_mul_f32 v[96:97], v[0:1], v[96:97]
	v_pk_mul_f32 v[98:99], v[2:3], v[98:99]
	v_pk_mul_f32 v[100:101], v[4:5], v[100:101]
	v_pk_mul_f32 v[102:103], v[6:7], v[102:103]
	v_pk_mul_f32 v[104:105], v[8:9], v[104:105]
	v_pk_mul_f32 v[106:107], v[10:11], v[106:107]
	v_pk_mul_f32 v[108:109], v[12:13], v[108:109]
	v_pk_mul_f32 v[110:111], v[14:15], v[110:111]
	v_cvt_pk_bf16_f32 v170, v96, v97
	v_cvt_pk_bf16_f32 v171, v98, v99
	v_cvt_pk_bf16_f32 v172, v100, v101
	v_cvt_pk_bf16_f32 v173, v102, v103
	v_cvt_pk_bf16_f32 v174, v104, v105
	v_cvt_pk_bf16_f32 v175, v106, v107
	v_cvt_pk_bf16_f32 v176, v108, v109
	v_cvt_pk_bf16_f32 v177, v110, v111
	v_lshlrev_b32_e32 v136, 16, v170
	v_and_b32_e32 v137, 0xffff0000, v170
	v_lshlrev_b32_e32 v138, 16, v171
	v_and_b32_e32 v139, 0xffff0000, v171
	v_lshlrev_b32_e32 v140, 16, v172
	v_and_b32_e32 v141, 0xffff0000, v172
	v_lshlrev_b32_e32 v142, 16, v173
	v_and_b32_e32 v143, 0xffff0000, v173
	v_lshlrev_b32_e32 v144, 16, v174
	v_and_b32_e32 v145, 0xffff0000, v174
	v_lshlrev_b32_e32 v146, 16, v175
	v_and_b32_e32 v147, 0xffff0000, v175
	v_lshlrev_b32_e32 v148, 16, v176
	v_and_b32_e32 v149, 0xffff0000, v176
	v_lshlrev_b32_e32 v150, 16, v177
	v_and_b32_e32 v151, 0xffff0000, v177
	v_pk_add_f32 v[112:113], v[80:81], v[136:137] neg_lo:[0,1] neg_hi:[0,1]
	v_pk_add_f32 v[114:115], v[82:83], v[138:139] neg_lo:[0,1] neg_hi:[0,1]
	v_pk_add_f32 v[116:117], v[84:85], v[140:141] neg_lo:[0,1] neg_hi:[0,1]
	v_pk_add_f32 v[118:119], v[86:87], v[142:143] neg_lo:[0,1] neg_hi:[0,1]
	v_pk_add_f32 v[120:121], v[88:89], v[144:145] neg_lo:[0,1] neg_hi:[0,1]
	v_pk_add_f32 v[122:123], v[90:91], v[146:147] neg_lo:[0,1] neg_hi:[0,1]
	v_pk_add_f32 v[124:125], v[92:93], v[148:149] neg_lo:[0,1] neg_hi:[0,1]
	v_pk_add_f32 v[126:127], v[94:95], v[150:151] neg_lo:[0,1] neg_hi:[0,1]
	global_store_dwordx2 v200, v[170:171], s[10:11]
	global_store_dwordx2 v200, v[172:173], s[10:11] offset:512
	global_store_dwordx2 v200, v[174:175], s[10:11] offset:1024
	global_store_dwordx2 v200, v[176:177], s[10:11] offset:1536
	v_pk_fma_f32 v[96:97], v[112:113], v[16:17], v[136:137]
	v_pk_fma_f32 v[98:99], v[114:115], v[18:19], v[138:139]
	v_pk_fma_f32 v[100:101], v[116:117], v[20:21], v[140:141]
	v_pk_fma_f32 v[102:103], v[118:119], v[22:23], v[142:143]
	v_pk_fma_f32 v[104:105], v[120:121], v[24:25], v[144:145]
	v_pk_fma_f32 v[106:107], v[122:123], v[26:27], v[146:147]
	v_pk_fma_f32 v[108:109], v[124:125], v[28:29], v[148:149]
	v_pk_fma_f32 v[110:111], v[126:127], v[30:31], v[150:151]
	v_cvt_pk_bf16_f32 v178, v96, v97
	v_cvt_pk_bf16_f32 v179, v98, v99
	v_cvt_pk_bf16_f32 v180, v100, v101
	v_cvt_pk_bf16_f32 v181, v102, v103
	v_cvt_pk_bf16_f32 v182, v104, v105
	v_cvt_pk_bf16_f32 v183, v106, v107
	v_cvt_pk_bf16_f32 v184, v108, v109
	v_cvt_pk_bf16_f32 v185, v110, v111
	global_store_dwordx2 v200, v[178:179], s[6:7]
	global_store_dwordx2 v200, v[180:181], s[6:7] offset:512
	global_store_dwordx2 v200, v[182:183], s[6:7] offset:1024
	global_store_dwordx2 v200, v[184:185], s[6:7] offset:1536
	v_pk_fma_f32 v[96:97], v[112:113], v[32:33], v[136:137]
	v_pk_fma_f32 v[98:99], v[114:115], v[34:35], v[138:139]
	v_pk_fma_f32 v[100:101], v[116:117], v[36:37], v[140:141]
	v_pk_fma_f32 v[102:103], v[118:119], v[38:39], v[142:143]
	v_pk_fma_f32 v[104:105], v[120:121], v[40:41], v[144:145]
	v_pk_fma_f32 v[106:107], v[122:123], v[42:43], v[146:147]
	v_pk_fma_f32 v[108:109], v[124:125], v[44:45], v[148:149]
	v_pk_fma_f32 v[110:111], v[126:127], v[46:47], v[150:151]
	v_cvt_pk_bf16_f32 v186, v96, v97
	v_cvt_pk_bf16_f32 v187, v98, v99
	v_cvt_pk_bf16_f32 v188, v100, v101
	v_cvt_pk_bf16_f32 v189, v102, v103
	v_cvt_pk_bf16_f32 v190, v104, v105
	v_cvt_pk_bf16_f32 v191, v106, v107
	v_cvt_pk_bf16_f32 v192, v108, v109
	v_cvt_pk_bf16_f32 v193, v110, v111
	global_store_dwordx2 v200, v[186:187], s[8:9]
	global_store_dwordx2 v200, v[188:189], s[8:9] offset:512
	global_store_dwordx2 v200, v[190:191], s[8:9] offset:1024
	global_store_dwordx2 v200, v[192:193], s[8:9] offset:1536
	v_add_u32_e32 v200, 0x800, v200
	s_waitcnt vmcnt(12)
; __device__ __forceinline__ u16 f2bf(float f) { return (u16)(pack2(f, f) & 0xFFFFu); }
; __device__ __forceinline__ float bf2f(u16 h) { return __uint_as_float(((unsigned)h) << 16); }
; __device__ __forceinline__ void norm_mix_phase(const float* x, const float* __restrict__ g, const float* __restrict__ mur, const float* __restrict__ muk,
;                                                u16* H, u16* XR, u16* XK) {
;     ...
;       const float4* xp = (const float4*)(x + (size_t)row * DM);
;       float4 v[4];
;       float ss = 0.f;
; #pragma unroll
;       for (int i = 0; i < 4; ++i) { v[i] = xp[i * 64 + lane]; ss += v[i].x * v[i].x + v[i].y * v[i].y + v[i].z * v[i].z + v[i].w * v[i].w; }
;       ss = wave_allreduce(ss);
;       const float rstd = rsqrtf(ss * (1.0f / DM) + 1e-6f);
;       float h[16];
; #pragma unroll
;       for (int i = 0; i < 4; ++i) {
;         const float4 gg = ((const float4*)g)[i * 64 + lane];
;         h[i * 4 + 0] = v[i].x * rstd * gg.x; h[i * 4 + 1] = v[i].y * rstd * gg.y; h[i * 4 + 2] = v[i].z * rstd * gg.z; h[i * 4 + 3] = v[i].w * rstd * gg.w;
;       }
;       if (row >= r0) {
; #pragma unroll
;         for (int i = 0; i < 4; ++i) {
;           const float4 mr = ((const float4*)mur)[i * 64 + lane], mk = ((const float4*)muk)[i * 64 + lane];
;           const float h0 = bf2f(f2bf(h[i * 4 + 0])), h1 = bf2f(f2bf(h[i * 4 + 1])), h2 = bf2f(f2bf(h[i * 4 + 2])), h3 = bf2f(f2bf(h[i * 4 + 3]));
;           const float p0 = bf2f(f2bf(hp[i * 4 + 0])), p1 = bf2f(f2bf(hp[i * 4 + 1])), p2 = bf2f(f2bf(hp[i * 4 + 2])), p3 = bf2f(f2bf(hp[i * 4 + 3]));
;           uint2 o; o.x = pack2(h[i * 4 + 0], h[i * 4 + 1]); o.y = pack2(h[i * 4 + 2], h[i * 4 + 3]);
;           ((uint2*)(H + (size_t)row * DM))[i * 64 + lane] = o;
;           o.x = pack2(h0 + (p0 - h0) * mr.x, h1 + (p1 - h1) * mr.y); o.y = pack2(h2 + (p2 - h2) * mr.z, h3 + (p3 - h3) * mr.w);
;           ((uint2*)(XR + (size_t)row * DM))[i * 64 + lane] = o;
;           o.x = pack2(h0 + (p0 - h0) * mk.x, h1 + (p1 - h1) * mk.y); o.y = pack2(h2 + (p2 - h2) * mk.z, h3 + (p3 - h3) * mk.w);
;           ((uint2*)(XK + (size_t)row * DM))[i * 64 + lane] = o;
	global_load_dwordx4 v[48:51], v199, s[12:13]
	global_load_dwordx4 v[52:55], v199, s[12:13] offset:1024
	global_load_dwordx4 v[56:59], v199, s[12:13] offset:2048
	global_load_dwordx4 v[60:63], v199, s[12:13] offset:3072
	v_add_u32_e32 v199, 0x1000, v199
	v_pk_mul_f32 v[128:129], v[64:65], v[64:65]
	v_pk_fma_f32 v[128:129], v[66:67], v[66:67], v[128:129]
	v_pk_fma_f32 v[128:129], v[68:69], v[68:69], v[128:129]
	v_pk_fma_f32 v[128:129], v[70:71], v[70:71], v[128:129]
	v_pk_fma_f32 v[128:129], v[72:73], v[72:73], v[128:129]
	v_pk_fma_f32 v[128:129], v[74:75], v[74:75], v[128:129]
	v_pk_fma_f32 v[128:129], v[76:77], v[76:77], v[128:129]
	v_pk_fma_f32 v[128:129], v[78:79], v[78:79], v[128:129]
	s_nop 0
	v_add_f32_e32 v128, v128, v129
	s_nop 1
	v_add_f32_dpp v128, v128, v128 quad_perm:[1,0,3,2] row_mask:0xf bank_mask:0xf bound_ctrl:1
	s_nop 1
	v_add_f32_dpp v128, v128, v128 quad_perm:[2,3,0,1] row_mask:0xf bank_mask:0xf bound_ctrl:1
	s_nop 1
	v_add_f32_dpp v128, v128, v128 row_half_mirror row_mask:0xf bank_mask:0xf bound_ctrl:1
	s_nop 1
	v_add_f32_dpp v128, v128, v128 row_mirror row_mask:0xf bank_mask:0xf bound_ctrl:1
	s_nop 1
	v_readlane_b32 s20, v128, 0
	v_readlane_b32 s21, v128, 32
	v_readlane_b32 s22, v128, 16
	v_readlane_b32 s23, v128, 48
	s_nop 1
	v_mov_b32_e32 v130, s22
	v_mov_b32_e32 v131, s23
	v_pk_add_f32 v[130:131], s[20:21], v[130:131]
	s_nop 0
	v_add_f32_e32 v130, v130, v131
	v_fma_f32 v130, v130, v194, v195
	v_rsq_f32_e32 v130, v130
	s_nop 0
	v_pk_mul_f32 v[96:97], v[64:65], v[130:131] op_sel_hi:[1,0]
	v_pk_mul_f32 v[98:99], v[66:67], v[130:131] op_sel_hi:[1,0]
	v_pk_mul_f32 v[100:101], v[68:69], v[130:131] op_sel_hi:[1,0]
	v_pk_mul_f32 v[102:103], v[70:71], v[130:131] op_sel_hi:[1,0]
	v_pk_mul_f32 v[104:105], v[72:73], v[130:131] op_sel_hi:[1,0]
	v_pk_mul_f32 v[106:107], v[74:75], v[130:131] op_sel_hi:[1,0]
	v_pk_mul_f32 v[108:109], v[76:77], v[130:131] op_sel_hi:[1,0]
	v_pk_mul_f32 v[110:111], v[78:79], v[130:131] op_sel_hi:[1,0]
	v_pk_mul_f32 v[96:97], v[0:1], v[96:97]
	v_pk_mul_f32 v[98:99], v[2:3], v[98:99]
	v_pk_mul_f32 v[100:101], v[4:5], v[100:101]
	v_pk_mul_f32 v[102:103], v[6:7], v[102:103]
	v_pk_mul_f32 v[104:105], v[8:9], v[104:105]
	v_pk_mul_f32 v[106:107], v[10:11], v[106:107]
	v_pk_mul_f32 v[108:109], v[12:13], v[108:109]
	v_pk_mul_f32 v[110:111], v[14:15], v[110:111]
	v_cvt_pk_bf16_f32 v170, v96, v97
	v_cvt_pk_bf16_f32 v171, v98, v99
	v_cvt_pk_bf16_f32 v172, v100, v101
	v_cvt_pk_bf16_f32 v173, v102, v103
	v_cvt_pk_bf16_f32 v174, v104, v105
	v_cvt_pk_bf16_f32 v175, v106, v107
	v_cvt_pk_bf16_f32 v176, v108, v109
	v_cvt_pk_bf16_f32 v177, v110, v111
	v_lshlrev_b32_e32 v80, 16, v170
	v_and_b32_e32 v81, 0xffff0000, v170
	v_lshlrev_b32_e32 v82, 16, v171
	v_and_b32_e32 v83, 0xffff0000, v171
	v_lshlrev_b32_e32 v84, 16, v172
	v_and_b32_e32 v85, 0xffff0000, v172
	v_lshlrev_b32_e32 v86, 16, v173
	v_and_b32_e32 v87, 0xffff0000, v173
	v_lshlrev_b32_e32 v88, 16, v174
	v_and_b32_e32 v89, 0xffff0000, v174
	v_lshlrev_b32_e32 v90, 16, v175
	v_and_b32_e32 v91, 0xffff0000, v175
	v_lshlrev_b32_e32 v92, 16, v176
	v_and_b32_e32 v93, 0xffff0000, v176
	v_lshlrev_b32_e32 v94, 16, v177
	v_and_b32_e32 v95, 0xffff0000, v177
	v_pk_add_f32 v[112:113], v[136:137], v[80:81] neg_lo:[0,1] neg_hi:[0,1]
	v_pk_add_f32 v[114:115], v[138:139], v[82:83] neg_lo:[0,1] neg_hi:[0,1]
	v_pk_add_f32 v[116:117], v[140:141], v[84:85] neg_lo:[0,1] neg_hi:[0,1]
	v_pk_add_f32 v[118:119], v[142:143], v[86:87] neg_lo:[0,1] neg_hi:[0,1]
	v_pk_add_f32 v[120:121], v[144:145], v[88:89] neg_lo:[0,1] neg_hi:[0,1]
	v_pk_add_f32 v[122:123], v[146:147], v[90:91] neg_lo:[0,1] neg_hi:[0,1]
	v_pk_add_f32 v[124:125], v[148:149], v[92:93] neg_lo:[0,1] neg_hi:[0,1]
	v_pk_add_f32 v[126:127], v[150:151], v[94:95] neg_lo:[0,1] neg_hi:[0,1]
	global_store_dwordx2 v200, v[170:171], s[10:11]
	global_store_dwordx2 v200, v[172:173], s[10:11] offset:512
	global_store_dwordx2 v200, v[174:175], s[10:11] offset:1024
	global_store_dwordx2 v200, v[176:177], s[10:11] offset:1536
	v_pk_fma_f32 v[96:97], v[112:113], v[16:17], v[80:81]
	v_pk_fma_f32 v[98:99], v[114:115], v[18:19], v[82:83]
	v_pk_fma_f32 v[100:101], v[116:117], v[20:21], v[84:85]
	v_pk_fma_f32 v[102:103], v[118:119], v[22:23], v[86:87]
	v_pk_fma_f32 v[104:105], v[120:121], v[24:25], v[88:89]
	v_pk_fma_f32 v[106:107], v[122:123], v[26:27], v[90:91]
	v_pk_fma_f32 v[108:109], v[124:125], v[28:29], v[92:93]
	v_pk_fma_f32 v[110:111], v[126:127], v[30:31], v[94:95]
	v_cvt_pk_bf16_f32 v178, v96, v97
	v_cvt_pk_bf16_f32 v179, v98, v99
	v_cvt_pk_bf16_f32 v180, v100, v101
	v_cvt_pk_bf16_f32 v181, v102, v103
	v_cvt_pk_bf16_f32 v182, v104, v105
	v_cvt_pk_bf16_f32 v183, v106, v107
	v_cvt_pk_bf16_f32 v184, v108, v109
	v_cvt_pk_bf16_f32 v185, v110, v111
	global_store_dwordx2 v200, v[178:179], s[6:7]
	global_store_dwordx2 v200, v[180:181], s[6:7] offset:512
	global_store_dwordx2 v200, v[182:183], s[6:7] offset:1024
	global_store_dwordx2 v200, v[184:185], s[6:7] offset:1536
	v_pk_fma_f32 v[96:97], v[112:113], v[32:33], v[80:81]
	v_pk_fma_f32 v[98:99], v[114:115], v[34:35], v[82:83]
	v_pk_fma_f32 v[100:101], v[116:117], v[36:37], v[84:85]
	v_pk_fma_f32 v[102:103], v[118:119], v[38:39], v[86:87]
	v_pk_fma_f32 v[104:105], v[120:121], v[40:41], v[88:89]
	v_pk_fma_f32 v[106:107], v[122:123], v[42:43], v[90:91]
	v_pk_fma_f32 v[108:109], v[124:125], v[44:45], v[92:93]
	v_pk_fma_f32 v[110:111], v[126:127], v[46:47], v[94:95]
	v_cvt_pk_bf16_f32 v186, v96, v97
	v_cvt_pk_bf16_f32 v187, v98, v99
	v_cvt_pk_bf16_f32 v188, v100, v101
	v_cvt_pk_bf16_f32 v189, v102, v103
	v_cvt_pk_bf16_f32 v190, v104, v105
	v_cvt_pk_bf16_f32 v191, v106, v107
	v_cvt_pk_bf16_f32 v192, v108, v109
	v_cvt_pk_bf16_f32 v193, v110, v111
	global_store_dwordx2 v200, v[186:187], s[8:9]
	global_store_dwordx2 v200, v[188:189], s[8:9] offset:512
	global_store_dwordx2 v200, v[190:191], s[8:9] offset:1024
	global_store_dwordx2 v200, v[192:193], s[8:9] offset:1536
	v_add_u32_e32 v200, 0x800, v200
	s_waitcnt vmcnt(12)
; __device__ __forceinline__ u16 f2bf(float f) { return (u16)(pack2(f, f) & 0xFFFFu); }
; __device__ __forceinline__ void norm_mix_phase(const float* x, const float* __restrict__ g, const float* __restrict__ mur, const float* __restrict__ muk,
;                                                u16* H, u16* XR, u16* XK) {
;     ...
;   for (int r0 = (bid * 8 + wid) * 16; r0 < MTOK; r0 += gridDim.x * 8 * 16) {
;     float hp[16];
; #pragma unroll
;     for (int i = 0; i < 16; ++i) hp[i] = 0.f;
;     const int rstart = ((r0 & (SEQ - 1)) == 0) ? r0 : r0 - 1;
;     for (int row = rstart; row < r0 + 16; ++row) {
;       const float4* xp = (const float4*)(x + (size_t)row * DM);
;       float4 v[4];
;       float ss = 0.f;
; #pragma unroll
;       for (int i = 0; i < 4; ++i) { v[i] = xp[i * 64 + lane]; ss += v[i].x * v[i].x + v[i].y * v[i].y + v[i].z * v[i].z + v[i].w * v[i].w; }
;       ss = wave_allreduce(ss);
;       const float rstd = rsqrtf(ss * (1.0f / DM) + 1e-6f);
;       float h[16];
; #pragma unroll
;       for (int i = 0; i < 4; ++i) {
;         const float4 gg = ((const float4*)g)[i * 64 + lane];
;         h[i * 4 + 0] = v[i].x * rstd * gg.x; h[i * 4 + 1] = v[i].y * rstd * gg.y; h[i * 4 + 2] = v[i].z * rstd * gg.z; h[i * 4 + 3] = v[i].w * rstd * gg.w;
;       }
;       if (row >= r0) {
; #pragma unroll
;         for (int i = 0; i < 4; ++i) {
;           const float4 mr = ((const float4*)mur)[i * 64 + lane], mk = ((const float4*)muk)[i * 64 + lane];
;           const float h0 = bf2f(f2bf(h[i * 4 + 0])), h1 = bf2f(f2bf(h[i * 4 + 1])), h2 = bf2f(f2bf(h[i * 4 + 2])), h3 = bf2f(f2bf(h[i * 4 + 3]));
;           const float p0 = bf2f(f2bf(hp[i * 4 + 0])), p1 = bf2f(f2bf(hp[i * 4 + 1])), p2 = bf2f(f2bf(hp[i * 4 + 2])), p3 = bf2f(f2bf(hp[i * 4 + 3]));
;           uint2 o; o.x = pack2(h[i * 4 + 0], h[i * 4 + 1]); o.y = pack2(h[i * 4 + 2], h[i * 4 + 3]);
;           ((uint2*)(H + (size_t)row * DM))[i * 64 + lane] = o;
;           o.x = pack2(h0 + (p0 - h0) * mr.x, h1 + (p1 - h1) * mr.y); o.y = pack2(h2 + (p2 - h2) * mr.z, h3 + (p3 - h3) * mr.w);
;           ((uint2*)(XR + (size_t)row * DM))[i * 64 + lane] = o;
;           o.x = pack2(h0 + (p0 - h0) * mk.x, h1 + (p1 - h1) * mk.y); o.y = pack2(h2 + (p2 - h2) * mk.z, h3 + (p3 - h3) * mk.w);
;           ((uint2*)(XK + (size_t)row * DM))[i * 64 + lane] = o;
	v_pk_mul_f32 v[128:129], v[48:49], v[48:49]
	v_pk_fma_f32 v[128:129], v[50:51], v[50:51], v[128:129]
	v_pk_fma_f32 v[128:129], v[52:53], v[52:53], v[128:129]
	v_pk_fma_f32 v[128:129], v[54:55], v[54:55], v[128:129]
	v_pk_fma_f32 v[128:129], v[56:57], v[56:57], v[128:129]
	v_pk_fma_f32 v[128:129], v[58:59], v[58:59], v[128:129]
	v_pk_fma_f32 v[128:129], v[60:61], v[60:61], v[128:129]
	v_pk_fma_f32 v[128:129], v[62:63], v[62:63], v[128:129]
	s_nop 0
	v_add_f32_e32 v128, v128, v129
	s_nop 1
	v_add_f32_dpp v128, v128, v128 quad_perm:[1,0,3,2] row_mask:0xf bank_mask:0xf bound_ctrl:1
	s_nop 1
	v_add_f32_dpp v128, v128, v128 quad_perm:[2,3,0,1] row_mask:0xf bank_mask:0xf bound_ctrl:1
	s_nop 1
	v_add_f32_dpp v128, v128, v128 row_half_mirror row_mask:0xf bank_mask:0xf bound_ctrl:1
	s_nop 1
	v_add_f32_dpp v128, v128, v128 row_mirror row_mask:0xf bank_mask:0xf bound_ctrl:1
	s_nop 1
	v_readlane_b32 s20, v128, 0
	v_readlane_b32 s21, v128, 32
	v_readlane_b32 s22, v128, 16
	v_readlane_b32 s23, v128, 48
	s_nop 1
	v_mov_b32_e32 v130, s22
	v_mov_b32_e32 v131, s23
	v_pk_add_f32 v[130:131], s[20:21], v[130:131]
	s_nop 0
	v_add_f32_e32 v130, v130, v131
	v_fma_f32 v130, v130, v194, v195
	v_rsq_f32_e32 v130, v130
	s_nop 0
	v_pk_mul_f32 v[96:97], v[48:49], v[130:131] op_sel_hi:[1,0]
	v_pk_mul_f32 v[98:99], v[50:51], v[130:131] op_sel_hi:[1,0]
	v_pk_mul_f32 v[100:101], v[52:53], v[130:131] op_sel_hi:[1,0]
	v_pk_mul_f32 v[102:103], v[54:55], v[130:131] op_sel_hi:[1,0]
	v_pk_mul_f32 v[104:105], v[56:57], v[130:131] op_sel_hi:[1,0]
	v_pk_mul_f32 v[106:107], v[58:59], v[130:131] op_sel_hi:[1,0]
	v_pk_mul_f32 v[108:109], v[60:61], v[130:131] op_sel_hi:[1,0]
	v_pk_mul_f32 v[110:111], v[62:63], v[130:131] op_sel_hi:[1,0]
	v_pk_mul_f32 v[96:97], v[0:1], v[96:97]
	v_pk_mul_f32 v[98:99], v[2:3], v[98:99]
	v_pk_mul_f32 v[100:101], v[4:5], v[100:101]
	v_pk_mul_f32 v[102:103], v[6:7], v[102:103]
	v_pk_mul_f32 v[104:105], v[8:9], v[104:105]
	v_pk_mul_f32 v[106:107], v[10:11], v[106:107]
	v_pk_mul_f32 v[108:109], v[12:13], v[108:109]
	v_pk_mul_f32 v[110:111], v[14:15], v[110:111]
	v_cvt_pk_bf16_f32 v170, v96, v97
	v_cvt_pk_bf16_f32 v171, v98, v99
	v_cvt_pk_bf16_f32 v172, v100, v101
	v_cvt_pk_bf16_f32 v173, v102, v103
	v_cvt_pk_bf16_f32 v174, v104, v105
	v_cvt_pk_bf16_f32 v175, v106, v107
	v_cvt_pk_bf16_f32 v176, v108, v109
	v_cvt_pk_bf16_f32 v177, v110, v111
	v_lshlrev_b32_e32 v136, 16, v170
	v_and_b32_e32 v137, 0xffff0000, v170
	v_lshlrev_b32_e32 v138, 16, v171
	v_and_b32_e32 v139, 0xffff0000, v171
	v_lshlrev_b32_e32 v140, 16, v172
	v_and_b32_e32 v141, 0xffff0000, v172
	v_lshlrev_b32_e32 v142, 16, v173
	v_and_b32_e32 v143, 0xffff0000, v173
	v_lshlrev_b32_e32 v144, 16, v174
	v_and_b32_e32 v145, 0xffff0000, v174
	v_lshlrev_b32_e32 v146, 16, v175
	v_and_b32_e32 v147, 0xffff0000, v175
	v_lshlrev_b32_e32 v148, 16, v176
	v_and_b32_e32 v149, 0xffff0000, v176
	v_lshlrev_b32_e32 v150, 16, v177
	v_and_b32_e32 v151, 0xffff0000, v177
	v_pk_add_f32 v[112:113], v[80:81], v[136:137] neg_lo:[0,1] neg_hi:[0,1]
	v_pk_add_f32 v[114:115], v[82:83], v[138:139] neg_lo:[0,1] neg_hi:[0,1]
	v_pk_add_f32 v[116:117], v[84:85], v[140:141] neg_lo:[0,1] neg_hi:[0,1]
	v_pk_add_f32 v[118:119], v[86:87], v[142:143] neg_lo:[0,1] neg_hi:[0,1]
	v_pk_add_f32 v[120:121], v[88:89], v[144:145] neg_lo:[0,1] neg_hi:[0,1]
	v_pk_add_f32 v[122:123], v[90:91], v[146:147] neg_lo:[0,1] neg_hi:[0,1]
	v_pk_add_f32 v[124:125], v[92:93], v[148:149] neg_lo:[0,1] neg_hi:[0,1]
	v_pk_add_f32 v[126:127], v[94:95], v[150:151] neg_lo:[0,1] neg_hi:[0,1]
	global_store_dwordx2 v200, v[170:171], s[10:11]
	global_store_dwordx2 v200, v[172:173], s[10:11] offset:512
	global_store_dwordx2 v200, v[174:175], s[10:11] offset:1024
	global_store_dwordx2 v200, v[176:177], s[10:11] offset:1536
	v_pk_fma_f32 v[96:97], v[112:113], v[16:17], v[136:137]
	v_pk_fma_f32 v[98:99], v[114:115], v[18:19], v[138:139]
	v_pk_fma_f32 v[100:101], v[116:117], v[20:21], v[140:141]
	v_pk_fma_f32 v[102:103], v[118:119], v[22:23], v[142:143]
	v_pk_fma_f32 v[104:105], v[120:121], v[24:25], v[144:145]
	v_pk_fma_f32 v[106:107], v[122:123], v[26:27], v[146:147]
	v_pk_fma_f32 v[108:109], v[124:125], v[28:29], v[148:149]
	v_pk_fma_f32 v[110:111], v[126:127], v[30:31], v[150:151]
	v_cvt_pk_bf16_f32 v178, v96, v97
	v_cvt_pk_bf16_f32 v179, v98, v99
	v_cvt_pk_bf16_f32 v180, v100, v101
	v_cvt_pk_bf16_f32 v181, v102, v103
	v_cvt_pk_bf16_f32 v182, v104, v105
	v_cvt_pk_bf16_f32 v183, v106, v107
	v_cvt_pk_bf16_f32 v184, v108, v109
	v_cvt_pk_bf16_f32 v185, v110, v111
	global_store_dwordx2 v200, v[178:179], s[6:7]
	global_store_dwordx2 v200, v[180:181], s[6:7] offset:512
	global_store_dwordx2 v200, v[182:183], s[6:7] offset:1024
	global_store_dwordx2 v200, v[184:185], s[6:7] offset:1536
	v_pk_fma_f32 v[96:97], v[112:113], v[32:33], v[136:137]
	v_pk_fma_f32 v[98:99], v[114:115], v[34:35], v[138:139]
	v_pk_fma_f32 v[100:101], v[116:117], v[36:37], v[140:141]
	v_pk_fma_f32 v[102:103], v[118:119], v[38:39], v[142:143]
	v_pk_fma_f32 v[104:105], v[120:121], v[40:41], v[144:145]
	v_pk_fma_f32 v[106:107], v[122:123], v[42:43], v[146:147]
	v_pk_fma_f32 v[108:109], v[124:125], v[44:45], v[148:149]
	v_pk_fma_f32 v[110:111], v[126:127], v[46:47], v[150:151]
	v_cvt_pk_bf16_f32 v186, v96, v97
	v_cvt_pk_bf16_f32 v187, v98, v99
	v_cvt_pk_bf16_f32 v188, v100, v101
	v_cvt_pk_bf16_f32 v189, v102, v103
	v_cvt_pk_bf16_f32 v190, v104, v105
	v_cvt_pk_bf16_f32 v191, v106, v107
	v_cvt_pk_bf16_f32 v192, v108, v109
	v_cvt_pk_bf16_f32 v193, v110, v111
	global_store_dwordx2 v200, v[186:187], s[8:9]
	global_store_dwordx2 v200, v[188:189], s[8:9] offset:512
	global_store_dwordx2 v200, v[190:191], s[8:9] offset:1024
	global_store_dwordx2 v200, v[192:193], s[8:9] offset:1536
	v_add_u32_e32 v200, 0x800, v200
	s_add_i32 s24, s24, s25
	s_cmp_lt_i32 s24, 0x8000
	s_cbranch_scc1 .Lnm_outer
